# adds rescheduled windowed-GQA tile loop (table row as MFMA C input) and pipelined loop in the 9th diff-attn unit
# baseline (speedup 1.0000x reference)
; #define LAS __attribute__((address_space(3)))
; __device__ __forceinline__ unsigned cvtpk(float lo, float hi) { f32x2_t v = {lo, hi}; bf16x2_t b = __builtin_convertvector(v, bf16x2_t); return __builtin_bit_cast(unsigned, b); }
; #define A_BAR() asm volatile("s_waitcnt lgkmcnt(0)\n\ts_barrier" ::: "memory")
; __device__ __forceinline__ void attn_unit_A(const AttnP& P, int u, LAS char* lds) {
;     ...
;     for (int t = 0; t < nt; ++t) {
;         const bool more = (t + 1 < nt);
;         if (more) { A_WRITE(bnext); if (t + 2 < nt) A_ISSUE(t + 2); }
;         int clsn = clsk;
;         if (more) { clsn = A_CLS(t + 1);
;             if (clsn != clsk) { const float dc = A_CVAL(clsn) - A_CVAL(clsk); clsk = clsn;
; #pragma unroll
;                 for (int r = 0; r < 16; ++r) negc[r] += dc; } }
;     ...
;         const LAS char* vbase = lds + bcur + 2 * AKS + vrow * AVP + vcolb;
;     ...
;         bf16x8 vfa[4], vfb[4];
;         A_VLOAD(vfa, 0);
;         __builtin_amdgcn_sched_barrier(0);
;         float sacc = 0.f;
; #pragma unroll
;         for (int r = 0; r < 16; ++r) { sa0[r] = __builtin_amdgcn_exp2f(sa0[r]); sa1[r] = __builtin_amdgcn_exp2f(sa1[r]); sacc += sa0[r] + sa1[r]; }
;         lrun += sacc;
;         bf16x8 pf[4];
;         { u32x4 a;
;           a.x = cvtpk(sa0[0], sa0[1]); a.y = cvtpk(sa0[2], sa0[3]); a.z = cvtpk(sa0[4], sa0[5]); a.w = cvtpk(sa0[6], sa0[7]); pf[0] = __builtin_bit_cast(bf16x8, a);
;           a.x = cvtpk(sa0[8], sa0[9]); a.y = cvtpk(sa0[10], sa0[11]); a.z = cvtpk(sa0[12], sa0[13]); a.w = cvtpk(sa0[14], sa0[15]); pf[1] = __builtin_bit_cast(bf16x8, a);
;           a.x = cvtpk(sa1[0], sa1[1]); a.y = cvtpk(sa1[2], sa1[3]); a.z = cvtpk(sa1[4], sa1[5]); a.w = cvtpk(sa1[6], sa1[7]); pf[2] = __builtin_bit_cast(bf16x8, a);
;           a.x = cvtpk(sa1[8], sa1[9]); a.y = cvtpk(sa1[10], sa1[11]); a.z = cvtpk(sa1[12], sa1[13]); a.w = cvtpk(sa1[14], sa1[15]); pf[3] = __builtin_bit_cast(bf16x8, a); }
;         __builtin_amdgcn_sched_barrier(0);
;         A_VLOAD(vfb, 1);
;         __builtin_amdgcn_sched_barrier(0);
;         A_VMMA(vfa, 0);
;         A_VLOAD(vfa, 2);
;         __builtin_amdgcn_sched_barrier(0);
;         A_VMMA(vfb, 1);
;         A_VLOAD(vfb, 3);
;         __builtin_amdgcn_sched_barrier(0);
;         A_VMMA(vfa, 2);
;         __builtin_amdgcn_sched_barrier(0);
;         A_VMMA(vfb, 3);
;     ...
;         __builtin_amdgcn_sched_barrier(0); A_BAR(); A_QKBLK();
.LBB0_749:
	v_add3_u32 v238, s28, v172, v160
	v_add3_u32 v239, s28, v174, v160
	s_waitcnt vmcnt(3)
	ds_write_b128 v238, v[156:159]
	s_waitcnt vmcnt(2)
	ds_write_b128 v238, v[152:155] offset:9216
	s_waitcnt vmcnt(1)
	ds_write_b128 v239, v[148:151] offset:18432
	s_waitcnt vmcnt(0)
	ds_write_b128 v239, v[144:147] offset:30720
	v_add_u32_e32 v238, s31, v175
	v_min_i32_e32 v238, 0x100f, v238
	v_mad_i64_i32 v[244:245], s[0:1], v238, s51, v[162:163]
	global_load_dwordx4 v[156:159], v[244:245], off offset:1024
	global_load_dwordx4 v[152:155], v[244:245], off offset:1152
	global_load_dwordx4 v[148:151], v[244:245], off offset:2048
	global_load_dwordx4 v[144:147], v[244:245], off offset:2176
	v_mov_b32_e32 v206, v96
	v_mov_b32_e32 v0, v112
	v_mov_b32_e32 v207, v97
	v_mov_b32_e32 v1, v113
	v_mov_b32_e32 v208, v98
	v_mov_b32_e32 v2, v114
	v_mov_b32_e32 v209, v99
	v_mov_b32_e32 v3, v115
	v_mov_b32_e32 v210, v100
	v_mov_b32_e32 v4, v116
	v_mov_b32_e32 v211, v101
	v_mov_b32_e32 v5, v117
	v_mov_b32_e32 v212, v102
	v_mov_b32_e32 v6, v118
	v_mov_b32_e32 v213, v103
	v_mov_b32_e32 v7, v119
	v_mov_b32_e32 v214, v104
	v_mov_b32_e32 v8, v120
	v_mov_b32_e32 v215, v105
	v_mov_b32_e32 v9, v121
	v_mov_b32_e32 v216, v106
	v_mov_b32_e32 v10, v122
	v_mov_b32_e32 v217, v107
	v_mov_b32_e32 v11, v123
	v_mov_b32_e32 v218, v108
	v_mov_b32_e32 v12, v124
	v_mov_b32_e32 v219, v109
	v_mov_b32_e32 v13, v125
	v_mov_b32_e32 v220, v110
	v_mov_b32_e32 v14, v126
	v_mov_b32_e32 v221, v111
	v_mov_b32_e32 v15, v127
	v_mov_b32_e32 v202, 0
	s_mov_b32 s35, 0x15000
	s_waitcnt lgkmcnt(0)
	s_barrier
.Latt2_loop:
	s_add_i32 s0, s27, s31
	s_add_i32 s30, s31, 64
	s_addk_i32 s0, 0xf021
	s_cmpk_gt_i32 s0, 0x7f
	s_cselect_b32 s0, 2, 1
	s_cmp_gt_i32 s30, s16
	s_cselect_b32 s29, s0, 0
	s_cmp_eq_u32 s29, s34
	s_cbranch_scc1 .Latt2_e_same
	s_cmp_eq_u32 s29, 2
	s_cselect_b32 s0, 1, 0
	s_lshl_b32 s0, s0, 10
	s_add_i32 s0, s0, 0x1f800
	s_cmp_eq_u32 s34, 2
	s_cselect_b32 s1, 1, 0
	s_lshl_b32 s1, s1, 10
	s_add_i32 s1, s1, 0x1f800
	v_mov_b32_e32 v238, s0
	v_mov_b32_e32 v239, s1
	ds_read_b32 v238, v238
	ds_read_b32 v239, v239
	s_cmp_eq_u32 s29, 1
	s_cselect_b32 s0, 0, 0x3f800000
	s_cmp_eq_u32 s34, 1
	s_cselect_b32 s1, 0, 0x3f800000
	s_waitcnt lgkmcnt(0)
	v_mul_f32_e32 v238, s0, v238
	v_mul_f32_e32 v239, s1, v239
	v_sub_f32_e32 v238, v238, v239
	v_add_f32_e32 v80, v80, v238
	v_add_f32_e32 v81, v81, v238
	v_add_f32_e32 v82, v82, v238
	v_add_f32_e32 v83, v83, v238
	v_add_f32_e32 v84, v84, v238
	v_add_f32_e32 v85, v85, v238
	v_add_f32_e32 v86, v86, v238
	v_add_f32_e32 v87, v87, v238
	v_add_f32_e32 v88, v88, v238
	v_add_f32_e32 v89, v89, v238
	v_add_f32_e32 v90, v90, v238
	v_add_f32_e32 v91, v91, v238
	v_add_f32_e32 v92, v92, v238
	v_add_f32_e32 v93, v93, v238
	v_add_f32_e32 v94, v94, v238
	v_add_f32_e32 v95, v95, v238
.Latt2_e_same:
	v_add_u32_e32 v203, s28, v164
	v_add_u32_e32 v235, s26, v176
	s_cmp_eq_u32 s29, 1
	s_cbranch_scc1 .Latt2_e_near
	ds_read_b128 v[178:181], v203
	ds_read_b128 v[182:185], v203 offset:4608
	ds_read_b128 v[186:189], v203 offset:32
	ds_read_b128 v[190:193], v203 offset:4640
	ds_read_b128 v[222:225], v203 offset:64
	ds_read_b128 v[226:229], v203 offset:4672
	ds_read_b128 v[230:233], v203 offset:96
	v_exp_f32_e32 v206, v206
	v_exp_f32_e32 v207, v207
	v_exp_f32_e32 v208, v208
	v_exp_f32_e32 v209, v209
	v_exp_f32_e32 v210, v210
	v_exp_f32_e32 v211, v211
	v_exp_f32_e32 v212, v212
	v_exp_f32_e32 v213, v213
	s_waitcnt lgkmcnt(6)
	v_mfma_f32_32x32x16_bf16 v[96:111], v[178:181], v[140:143], v[80:95]
	ds_read_b128 v[178:181], v203 offset:4704
	v_add_f32_e32 v173, v173, v206
	v_add_f32_e32 v202, v202, v207
	v_add_f32_e32 v173, v173, v208
	v_add_f32_e32 v202, v202, v209
	v_exp_f32_e32 v214, v214
	s_waitcnt lgkmcnt(6)
	v_mfma_f32_32x32x16_bf16 v[112:127], v[182:185], v[140:143], v[80:95]
	ds_read_b64_tr_b16 v[182:183], v235 offset:18432
	ds_read_b64_tr_b16 v[184:185], v235 offset:19968
	v_add_f32_e32 v173, v173, v210
	v_add_f32_e32 v202, v202, v211
	v_add_f32_e32 v173, v173, v212
	v_add_f32_e32 v202, v202, v213
	v_exp_f32_e32 v215, v215
	s_branch .Latt2_e_join
.Latt2_e_near:
	v_add_u32_e32 v238, s31, v177
	s_add_i32 s0, 0, 0x1f800
	v_add_u32_e32 v96, 0xfffff040, v238
	v_med3_i32 v96, v96, s87, v240
	v_lshl_add_u32 v96, v96, 2, s0
	v_add_u32_e32 v97, 0xfffff041, v238
	v_med3_i32 v97, v97, s87, v240
	v_lshl_add_u32 v97, v97, 2, s0
	v_add_u32_e32 v98, 0xfffff042, v238
	v_med3_i32 v98, v98, s87, v240
	v_lshl_add_u32 v98, v98, 2, s0
	v_add_u32_e32 v99, 0xfffff043, v238
	v_med3_i32 v99, v99, s87, v240
	v_lshl_add_u32 v99, v99, 2, s0
	v_add_u32_e32 v100, 0xfffff048, v238
	v_med3_i32 v100, v100, s87, v240
	v_lshl_add_u32 v100, v100, 2, s0
	v_add_u32_e32 v101, 0xfffff049, v238
	v_med3_i32 v101, v101, s87, v240
	v_lshl_add_u32 v101, v101, 2, s0
	v_add_u32_e32 v102, 0xfffff04a, v238
	v_med3_i32 v102, v102, s87, v240
	v_lshl_add_u32 v102, v102, 2, s0
	v_add_u32_e32 v103, 0xfffff04b, v238
	v_med3_i32 v103, v103, s87, v240
	v_lshl_add_u32 v103, v103, 2, s0
	v_add_u32_e32 v104, 0xfffff050, v238
	v_med3_i32 v104, v104, s87, v240
	v_lshl_add_u32 v104, v104, 2, s0
	v_add_u32_e32 v105, 0xfffff051, v238
	v_med3_i32 v105, v105, s87, v240
	v_lshl_add_u32 v105, v105, 2, s0
	v_add_u32_e32 v106, 0xfffff052, v238
	v_med3_i32 v106, v106, s87, v240
	v_lshl_add_u32 v106, v106, 2, s0
	v_add_u32_e32 v107, 0xfffff053, v238
	v_med3_i32 v107, v107, s87, v240
	v_lshl_add_u32 v107, v107, 2, s0
	v_add_u32_e32 v108, 0xfffff058, v238
	v_med3_i32 v108, v108, s87, v240
	v_lshl_add_u32 v108, v108, 2, s0
	v_add_u32_e32 v109, 0xfffff059, v238
	v_med3_i32 v109, v109, s87, v240
	v_lshl_add_u32 v109, v109, 2, s0
	v_add_u32_e32 v110, 0xfffff05a, v238
; #define LAS __attribute__((address_space(3)))
; #define A_VLOAD(dst, d) do { const LAS char* vb_ = vbase + ((d) >> 1) * AVS + ((d) & 1) * 64; \
;         _Pragma("unroll") for (int ks = 0; ks < 4; ++ks) { const s16x4 vl_ = vtr(vb_ + (16 * ks) * AVP), vh_ = vtr(vb_ + (16 * ks + 8) * AVP); \
;             dst[ks] = (bf16x8){vl_[0], vl_[1], vl_[2], vl_[3], vh_[0], vh_[1], vh_[2], vh_[3]}; } } while (0)
; __device__ __forceinline__ void attn_unit_A(const AttnP& P, int u, LAS char* lds) {
;     ...
;         const LAS char* vbase = lds + bcur + 2 * AKS + vrow * AVP + vcolb;
;     ...
;         bf16x8 vfa[4], vfb[4];
;         A_VLOAD(vfa, 0);
;         __builtin_amdgcn_sched_barrier(0);
;         float sacc = 0.f;
; #pragma unroll
;         for (int r = 0; r < 16; ++r) { sa0[r] = __builtin_amdgcn_exp2f(sa0[r]); sa1[r] = __builtin_amdgcn_exp2f(sa1[r]); sacc += sa0[r] + sa1[r]; }
	v_med3_i32 v110, v110, s87, v240
	v_lshl_add_u32 v110, v110, 2, s0
	v_add_u32_e32 v111, 0xfffff05b, v238
	v_med3_i32 v111, v111, s87, v240
	v_lshl_add_u32 v111, v111, 2, s0
	ds_read_b32 v96, v96 offset:512
	ds_read_b32 v97, v97 offset:512
	ds_read_b32 v98, v98 offset:512
	ds_read_b32 v99, v99 offset:512
	ds_read_b32 v100, v100 offset:512
	ds_read_b32 v101, v101 offset:512
	ds_read_b32 v102, v102 offset:512
	ds_read_b32 v103, v103 offset:512
	ds_read_b32 v104, v104 offset:512
	ds_read_b32 v105, v105 offset:512
	ds_read_b32 v106, v106 offset:512
	ds_read_b32 v107, v107 offset:512
	ds_read_b32 v108, v108 offset:512
	ds_read_b32 v109, v109 offset:512
	ds_read_b32 v110, v110 offset:512
	ds_read_b32 v111, v111 offset:512
	v_add_u32_e32 v112, 0xfffff060, v238
	v_med3_i32 v112, v112, s87, v240
	v_lshl_add_u32 v112, v112, 2, s0
	v_add_u32_e32 v113, 0xfffff061, v238
	v_med3_i32 v113, v113, s87, v240
	v_lshl_add_u32 v113, v113, 2, s0
	v_add_u32_e32 v114, 0xfffff062, v238
	v_med3_i32 v114, v114, s87, v240
	v_lshl_add_u32 v114, v114, 2, s0
	v_add_u32_e32 v115, 0xfffff063, v238
	v_med3_i32 v115, v115, s87, v240
	v_lshl_add_u32 v115, v115, 2, s0
	v_add_u32_e32 v116, 0xfffff068, v238
	v_med3_i32 v116, v116, s87, v240
	v_lshl_add_u32 v116, v116, 2, s0
	v_add_u32_e32 v117, 0xfffff069, v238
	v_med3_i32 v117, v117, s87, v240
	v_lshl_add_u32 v117, v117, 2, s0
	v_add_u32_e32 v118, 0xfffff06a, v238
	v_med3_i32 v118, v118, s87, v240
	v_lshl_add_u32 v118, v118, 2, s0
	v_add_u32_e32 v119, 0xfffff06b, v238
	v_med3_i32 v119, v119, s87, v240
	v_lshl_add_u32 v119, v119, 2, s0
	v_add_u32_e32 v120, 0xfffff070, v238
	v_med3_i32 v120, v120, s87, v240
	v_lshl_add_u32 v120, v120, 2, s0
	v_add_u32_e32 v121, 0xfffff071, v238
	v_med3_i32 v121, v121, s87, v240
	v_lshl_add_u32 v121, v121, 2, s0
	v_add_u32_e32 v122, 0xfffff072, v238
	v_med3_i32 v122, v122, s87, v240
	v_lshl_add_u32 v122, v122, 2, s0
	v_add_u32_e32 v123, 0xfffff073, v238
	v_med3_i32 v123, v123, s87, v240
	v_lshl_add_u32 v123, v123, 2, s0
	v_add_u32_e32 v124, 0xfffff078, v238
	v_med3_i32 v124, v124, s87, v240
	v_lshl_add_u32 v124, v124, 2, s0
	v_add_u32_e32 v125, 0xfffff079, v238
	v_med3_i32 v125, v125, s87, v240
	v_lshl_add_u32 v125, v125, 2, s0
	v_add_u32_e32 v126, 0xfffff07a, v238
	v_med3_i32 v126, v126, s87, v240
	v_lshl_add_u32 v126, v126, 2, s0
	v_add_u32_e32 v127, 0xfffff07b, v238
	v_med3_i32 v127, v127, s87, v240
	v_lshl_add_u32 v127, v127, 2, s0
	ds_read_b32 v112, v112 offset:512
	ds_read_b32 v113, v113 offset:512
	ds_read_b32 v114, v114 offset:512
	ds_read_b32 v115, v115 offset:512
	ds_read_b32 v116, v116 offset:512
	ds_read_b32 v117, v117 offset:512
	ds_read_b32 v118, v118 offset:512
	ds_read_b32 v119, v119 offset:512
	ds_read_b32 v120, v120 offset:512
	ds_read_b32 v121, v121 offset:512
	ds_read_b32 v122, v122 offset:512
	ds_read_b32 v123, v123 offset:512
	ds_read_b32 v124, v124 offset:512
	ds_read_b32 v125, v125 offset:512
	ds_read_b32 v126, v126 offset:512
	ds_read_b32 v127, v127 offset:512
	s_waitcnt lgkmcnt(0)
	v_add_f32_e32 v96, v96, v80
	v_add_f32_e32 v97, v97, v80
	v_add_f32_e32 v98, v98, v80
	v_add_f32_e32 v99, v99, v80
	v_add_f32_e32 v100, v100, v80
	v_add_f32_e32 v101, v101, v80
	v_add_f32_e32 v102, v102, v80
	v_add_f32_e32 v103, v103, v80
	v_add_f32_e32 v104, v104, v80
	v_add_f32_e32 v105, v105, v80
	v_add_f32_e32 v106, v106, v80
	v_add_f32_e32 v107, v107, v80
	v_add_f32_e32 v108, v108, v80
	v_add_f32_e32 v109, v109, v80
	v_add_f32_e32 v110, v110, v80
	v_add_f32_e32 v111, v111, v80
	v_add_f32_e32 v112, v112, v80
	v_add_f32_e32 v113, v113, v80
	v_add_f32_e32 v114, v114, v80
	v_add_f32_e32 v115, v115, v80
	v_add_f32_e32 v116, v116, v80
	v_add_f32_e32 v117, v117, v80
	v_add_f32_e32 v118, v118, v80
	v_add_f32_e32 v119, v119, v80
	v_add_f32_e32 v120, v120, v80
	v_add_f32_e32 v121, v121, v80
	v_add_f32_e32 v122, v122, v80
	v_add_f32_e32 v123, v123, v80
	v_add_f32_e32 v124, v124, v80
	v_add_f32_e32 v125, v125, v80
	v_add_f32_e32 v126, v126, v80
	v_add_f32_e32 v127, v127, v80
	ds_read_b128 v[178:181], v203
	ds_read_b128 v[182:185], v203 offset:4608
	ds_read_b128 v[186:189], v203 offset:32
	ds_read_b128 v[190:193], v203 offset:4640
	ds_read_b128 v[222:225], v203 offset:64
	ds_read_b128 v[226:229], v203 offset:4672
	ds_read_b128 v[230:233], v203 offset:96
	v_exp_f32_e32 v206, v206
	v_exp_f32_e32 v207, v207
	v_exp_f32_e32 v208, v208
	v_exp_f32_e32 v209, v209
	v_exp_f32_e32 v210, v210
	v_exp_f32_e32 v211, v211
	v_exp_f32_e32 v212, v212
	v_exp_f32_e32 v213, v213
	s_waitcnt lgkmcnt(6)
	v_mfma_f32_32x32x16_bf16 v[96:111], v[178:181], v[140:143], v[96:111]
	ds_read_b128 v[178:181], v203 offset:4704
	v_add_f32_e32 v173, v173, v206
	v_add_f32_e32 v202, v202, v207
	v_add_f32_e32 v173, v173, v208
	v_add_f32_e32 v202, v202, v209
	v_exp_f32_e32 v214, v214
	s_waitcnt lgkmcnt(6)
	v_mfma_f32_32x32x16_bf16 v[112:127], v[182:185], v[140:143], v[112:127]
	ds_read_b64_tr_b16 v[182:183], v235 offset:18432
	ds_read_b64_tr_b16 v[184:185], v235 offset:19968
	v_add_f32_e32 v173, v173, v210
	v_add_f32_e32 v202, v202, v211
	v_add_f32_e32 v173, v173, v212
	v_add_f32_e32 v202, v202, v213
	v_exp_f32_e32 v215, v215
; #define LAS __attribute__((address_space(3)))
; __device__ __forceinline__ void attn_unit_A(const AttnP& P, int u, LAS char* lds) {
;     ...
;         const LAS char* vbase = lds + bcur + 2 * AKS + vrow * AVP + vcolb;
;     ...
;         bf16x8 vfa[4], vfb[4];
;         A_VLOAD(vfa, 0);
;         __builtin_amdgcn_sched_barrier(0);
;         float sacc = 0.f;
; #pragma unroll
;         for (int r = 0; r < 16; ++r) { sa0[r] = __builtin_amdgcn_exp2f(sa0[r]); sa1[r] = __builtin_amdgcn_exp2f(sa1[r]); sacc += sa0[r] + sa1[r]; }
;         lrun += sacc;
;         bf16x8 pf[4];
;         { u32x4 a;
;           a.x = cvtpk(sa0[0], sa0[1]); a.y = cvtpk(sa0[2], sa0[3]); a.z = cvtpk(sa0[4], sa0[5]); a.w = cvtpk(sa0[6], sa0[7]); pf[0] = __builtin_bit_cast(bf16x8, a);
;           a.x = cvtpk(sa0[8], sa0[9]); a.y = cvtpk(sa0[10], sa0[11]); a.z = cvtpk(sa0[12], sa0[13]); a.w = cvtpk(sa0[14], sa0[15]); pf[1] = __builtin_bit_cast(bf16x8, a);
;           a.x = cvtpk(sa1[0], sa1[1]); a.y = cvtpk(sa1[2], sa1[3]); a.z = cvtpk(sa1[4], sa1[5]); a.w = cvtpk(sa1[6], sa1[7]); pf[2] = __builtin_bit_cast(bf16x8, a);
;           a.x = cvtpk(sa1[8], sa1[9]); a.y = cvtpk(sa1[10], sa1[11]); a.z = cvtpk(sa1[12], sa1[13]); a.w = cvtpk(sa1[14], sa1[15]); pf[3] = __builtin_bit_cast(bf16x8, a); }
;         __builtin_amdgcn_sched_barrier(0);
;         A_VLOAD(vfb, 1);
;         __builtin_amdgcn_sched_barrier(0);
;         A_VMMA(vfa, 0);
;         A_VLOAD(vfa, 2);
;         __builtin_amdgcn_sched_barrier(0);
;         A_VMMA(vfb, 1);
;         A_VLOAD(vfb, 3);
;         __builtin_amdgcn_sched_barrier(0);
;         A_VMMA(vfa, 2);
;         __builtin_amdgcn_sched_barrier(0);
;         A_VMMA(vfb, 3);
;     ...
;         __builtin_amdgcn_sched_barrier(0); A_BAR(); A_QKBLK();
;     ...
;         if (more) {
;             if (clsn == 1) A_NEAR(sa0, sa1, t + 1);
;             float mx_; A_ROWMAX(sa0, sa1, mx_);
;             if (__any(mx_ > 8.0f)) { const float dl = fmaxf(mx_, 0.f); const float f_ = __builtin_amdgcn_exp2f(-dl); lrun *= f_;
; #pragma unroll
;                 for (int r = 0; r < 16; ++r) { sa0[r] -= dl; sa1[r] -= dl; negc[r] -= dl; }
; #pragma unroll
;                 for (int d = 0; d < 4; ++d)
; #pragma unroll
;                     for (int r = 0; r < 16; ++r) o[d][r] *= f_; }
;         }
;         bcur = bnext; bnext = bnext + ABUF; if (bnext == 3 * ABUF) bnext = 0;
.Latt2_e_join:
	s_waitcnt lgkmcnt(7)
	v_mfma_f32_32x32x16_bf16 v[96:111], v[186:189], v[136:139], v[96:111]
	ds_read_b64_tr_b16 v[186:187], v235 offset:18496
	ds_read_b64_tr_b16 v[188:189], v235 offset:20032
	v_cvt_pk_bf16_f32 v206, v206, v207
	v_cvt_pk_bf16_f32 v207, v208, v209
	v_cvt_pk_bf16_f32 v208, v210, v211
	v_cvt_pk_bf16_f32 v209, v212, v213
	v_exp_f32_e32 v216, v216
	s_waitcnt lgkmcnt(8)
	v_mfma_f32_32x32x16_bf16 v[112:127], v[190:193], v[136:139], v[112:127]
	ds_read_b64_tr_b16 v[190:191], v235 offset:30720
	ds_read_b64_tr_b16 v[192:193], v235 offset:32256
	v_exp_f32_e32 v217, v217
	v_exp_f32_e32 v218, v218
	v_exp_f32_e32 v219, v219
	s_waitcnt lgkmcnt(9)
	v_mfma_f32_32x32x16_bf16 v[96:111], v[222:225], v[132:135], v[96:111]
	ds_read_b64_tr_b16 v[222:223], v235 offset:30784
	ds_read_b64_tr_b16 v[224:225], v235 offset:32320
	v_exp_f32_e32 v220, v220
	v_exp_f32_e32 v221, v221
	v_add_f32_e32 v173, v173, v214
	v_add_f32_e32 v202, v202, v215
	s_waitcnt lgkmcnt(10)
	v_mfma_f32_32x32x16_bf16 v[112:127], v[226:229], v[132:135], v[112:127]
	ds_read_b64_tr_b16 v[226:227], v235 offset:21504
	ds_read_b64_tr_b16 v[228:229], v235 offset:23040
	v_add_f32_e32 v173, v173, v216
	v_add_f32_e32 v202, v202, v217
	v_add_f32_e32 v173, v173, v218
	v_add_f32_e32 v202, v202, v219
	v_add_f32_e32 v173, v173, v220
	v_add_f32_e32 v202, v202, v221
	s_waitcnt lgkmcnt(11)
	v_mfma_f32_32x32x16_bf16 v[96:111], v[230:233], v[128:131], v[96:111]
	ds_read_b64_tr_b16 v[230:231], v235 offset:21568
	ds_read_b64_tr_b16 v[232:233], v235 offset:23104
	v_cvt_pk_bf16_f32 v210, v214, v215
	v_cvt_pk_bf16_f32 v211, v216, v217
	v_cvt_pk_bf16_f32 v212, v218, v219
	v_cvt_pk_bf16_f32 v213, v220, v221
	v_exp_f32_e32 v0, v0
	s_waitcnt lgkmcnt(12)
	v_mfma_f32_32x32x16_bf16 v[112:127], v[178:181], v[128:131], v[112:127]
	ds_read_b64_tr_b16 v[178:179], v235 offset:33792
	ds_read_b64_tr_b16 v[180:181], v235 offset:35328
	v_exp_f32_e32 v1, v1
	v_exp_f32_e32 v2, v2
	v_exp_f32_e32 v3, v3
	s_waitcnt lgkmcnt(12)
	v_mfma_f32_32x32x16_bf16 v[64:79], v[182:185], v[206:209], v[64:79]
	ds_read_b64_tr_b16 v[182:183], v235 offset:33856
	ds_read_b64_tr_b16 v[184:185], v235 offset:35392
	v_exp_f32_e32 v4, v4
	v_exp_f32_e32 v5, v5
	v_exp_f32_e32 v6, v6
	s_waitcnt lgkmcnt(12)
	v_mfma_f32_32x32x16_bf16 v[48:63], v[186:189], v[206:209], v[48:63]
	ds_read_b64_tr_b16 v[186:187], v235 offset:24576
	ds_read_b64_tr_b16 v[188:189], v235 offset:26112
	v_exp_f32_e32 v7, v7
	v_add_f32_e32 v173, v173, v0
	v_add_f32_e32 v202, v202, v1
	v_add_f32_e32 v173, v173, v2
	v_add_f32_e32 v202, v202, v3
	s_waitcnt lgkmcnt(12)
	v_mfma_f32_32x32x16_bf16 v[32:47], v[190:193], v[206:209], v[32:47]
	ds_read_b64_tr_b16 v[190:191], v235 offset:24640
	ds_read_b64_tr_b16 v[192:193], v235 offset:26176
	v_add_f32_e32 v173, v173, v4
	v_add_f32_e32 v202, v202, v5
	v_add_f32_e32 v173, v173, v6
	v_add_f32_e32 v202, v202, v7
	v_exp_f32_e32 v8, v8
	s_waitcnt lgkmcnt(12)
	v_mfma_f32_32x32x16_bf16 v[16:31], v[222:225], v[206:209], v[16:31]
	ds_read_b64_tr_b16 v[222:223], v235 offset:36864
	ds_read_b64_tr_b16 v[224:225], v235 offset:38400
	v_cvt_pk_bf16_f32 v214, v0, v1
	v_cvt_pk_bf16_f32 v215, v2, v3
	v_cvt_pk_bf16_f32 v216, v4, v5
	v_cvt_pk_bf16_f32 v217, v6, v7
	v_exp_f32_e32 v9, v9
	s_waitcnt lgkmcnt(12)
	v_mfma_f32_32x32x16_bf16 v[64:79], v[226:229], v[210:213], v[64:79]
	ds_read_b64_tr_b16 v[226:227], v235 offset:36928
	ds_read_b64_tr_b16 v[228:229], v235 offset:38464
	v_exp_f32_e32 v10, v10
	v_exp_f32_e32 v11, v11
	v_exp_f32_e32 v12, v12
	s_waitcnt lgkmcnt(12)
	v_mfma_f32_32x32x16_bf16 v[48:63], v[230:233], v[210:213], v[48:63]
	ds_read_b64_tr_b16 v[230:231], v235 offset:27648
	ds_read_b64_tr_b16 v[232:233], v235 offset:29184
	v_exp_f32_e32 v13, v13
	v_exp_f32_e32 v14, v14
	v_exp_f32_e32 v15, v15
	s_waitcnt lgkmcnt(12)
	v_mfma_f32_32x32x16_bf16 v[32:47], v[178:181], v[210:213], v[32:47]
	ds_read_b64_tr_b16 v[178:179], v235 offset:27712
	ds_read_b64_tr_b16 v[180:181], v235 offset:29248
	v_add_f32_e32 v173, v173, v8
	v_add_f32_e32 v202, v202, v9
	v_add_f32_e32 v173, v173, v10
	v_add_f32_e32 v202, v202, v11
	v_add_f32_e32 v173, v173, v12
	v_add_f32_e32 v202, v202, v13
	s_waitcnt lgkmcnt(12)
	v_mfma_f32_32x32x16_bf16 v[16:31], v[182:185], v[210:213], v[16:31]
	ds_read_b64_tr_b16 v[182:183], v235 offset:39936
	ds_read_b64_tr_b16 v[184:185], v235 offset:41472
	v_add_f32_e32 v173, v173, v14
	v_add_f32_e32 v202, v202, v15
	v_cvt_pk_bf16_f32 v218, v8, v9
	v_cvt_pk_bf16_f32 v219, v10, v11
	v_cvt_pk_bf16_f32 v220, v12, v13
	v_cvt_pk_bf16_f32 v221, v14, v15
	s_waitcnt lgkmcnt(12)
	v_mfma_f32_32x32x16_bf16 v[64:79], v[186:189], v[214:217], v[64:79]
	ds_read_b64_tr_b16 v[186:187], v235 offset:40000
	ds_read_b64_tr_b16 v[188:189], v235 offset:41536
	v_max3_f32 v243, v96, v97, v98
	v_max3_f32 v239, v112, v113, v114
	v_max3_f32 v243, v243, v99, v100
	v_max3_f32 v239, v239, v115, v116
	v_max3_f32 v243, v243, v101, v102
	s_waitcnt lgkmcnt(12)
	v_mfma_f32_32x32x16_bf16 v[48:63], v[190:193], v[214:217], v[48:63]
	v_max3_f32 v239, v239, v117, v118
	v_max3_f32 v243, v243, v103, v104
	v_max3_f32 v239, v239, v119, v120
	v_max3_f32 v243, v243, v105, v106
	v_max3_f32 v239, v239, v121, v122
	v_max3_f32 v243, v243, v107, v108
	s_waitcnt lgkmcnt(10)
	v_mfma_f32_32x32x16_bf16 v[32:47], v[222:225], v[214:217], v[32:47]
	v_max3_f32 v239, v239, v123, v124
	v_max3_f32 v243, v243, v109, v110
	v_max3_f32 v239, v239, v125, v126
	v_max_f32_e32 v243, v243, v111
	v_max_f32_e32 v239, v239, v127
	v_max_f32_e32 v243, v243, v239
	s_waitcnt lgkmcnt(8)
	v_mfma_f32_32x32x16_bf16 v[16:31], v[226:229], v[214:217], v[16:31]
	s_waitcnt vmcnt(0)
	v_add3_u32 v238, s35, v172, v160
	v_add3_u32 v239, s35, v174, v160
	ds_write_b128 v238, v[156:159]
	ds_write_b128 v238, v[152:155] offset:9216
	s_waitcnt lgkmcnt(8)
	v_mfma_f32_32x32x16_bf16 v[64:79], v[230:233], v[218:221], v[64:79]
	ds_write_b128 v239, v[148:151] offset:18432
	ds_write_b128 v239, v[144:147] offset:30720
	v_mov_b32_e32 v239, v243
	s_min_i32 s0, s30, 0xf80
	v_add_u32_e32 v238, s0, v175
	v_min_i32_e32 v238, 0x100f, v238
	s_waitcnt lgkmcnt(8)
	v_mfma_f32_32x32x16_bf16 v[48:63], v[178:181], v[218:221], v[48:63]
	v_permlane32_swap_b32_e32 v243, v239
	v_mad_i64_i32 v[244:245], s[0:1], v238, s51, v[162:163]
	global_load_dwordx4 v[156:159], v[244:245], off offset:1024
	global_load_dwordx4 v[152:155], v[244:245], off offset:1152
	s_waitcnt lgkmcnt(6)
	v_mfma_f32_32x32x16_bf16 v[32:47], v[182:185], v[218:221], v[32:47]
	global_load_dwordx4 v[148:151], v[244:245], off offset:2048
	global_load_dwordx4 v[144:147], v[244:245], off offset:2176
	v_max_f32_e32 v243, v243, v239
	s_waitcnt lgkmcnt(4)
	v_mfma_f32_32x32x16_bf16 v[16:31], v[186:189], v[218:221], v[16:31]
	s_mov_b32 s34, s29
	s_mov_b32 s26, s28
	s_mov_b32 s28, s35
	s_add_i32 s0, s35, 0xa800
	s_cmp_lg_u32 s0, 0x1f800
	s_cselect_b32 s35, s0, 0
	s_mov_b32 s31, s30
	v_cmp_lt_f32_e32 vcc, s10, v243
	s_cbranch_vccz .Latt2_e_noresc
; #define A_ISSUE(t) do { int tok_ = 64 * (t) + lrow; tok_ = tok_ > LT - 1 ? LT - 1 : tok_; const bf16_t* src_ = pb + (size_t)tok_ * INC; \
;         pre[0] = *(const u32x4*)(src_ + 512); pre[1] = *(const u32x4*)(src_ + 576); pre[2] = *(const u32x4*)(src_ + 1024); pre[3] = *(const u32x4*)(src_ + 1088); } while (0)
; #define A_WRITE(bufo) do { LAS char* d_ = lds + (bufo); \
;         *(LAS u32x4*)(d_ + lrow * AKP + lch * 16) = pre[0]; *(LAS u32x4*)(d_ + AKS + lrow * AKP + lch * 16) = pre[1]; \
;         *(LAS u32x4*)(d_ + 2 * AKS + lrow * AVP + lch * 16) = pre[2]; *(LAS u32x4*)(d_ + 2 * AKS + AVS + lrow * AVP + lch * 16) = pre[3]; } while (0)
; __device__ __forceinline__ void attn_unit_A(const AttnP& P, int u, LAS char* lds) {
;     ...
;     for (int t = 0; t < nt; ++t) {
;         const bool more = (t + 1 < nt);
;         if (more) { A_WRITE(bnext); if (t + 2 < nt) A_ISSUE(t + 2); }
;         int clsn = clsk;
;         if (more) { clsn = A_CLS(t + 1);
;             if (clsn != clsk) { const float dc = A_CVAL(clsn) - A_CVAL(clsk); clsk = clsn;
; #pragma unroll
;                 for (int r = 0; r < 16; ++r) negc[r] += dc; } }
;     ...
;         if (more) {
;             if (clsn == 1) A_NEAR(sa0, sa1, t + 1);
;             float mx_; A_ROWMAX(sa0, sa1, mx_);
;             if (__any(mx_ > 8.0f)) { const float dl = fmaxf(mx_, 0.f); const float f_ = __builtin_amdgcn_exp2f(-dl); lrun *= f_;
; #pragma unroll
;                 for (int r = 0; r < 16; ++r) { sa0[r] -= dl; sa1[r] -= dl; negc[r] -= dl; }
; #pragma unroll
;                 for (int d = 0; d < 4; ++d)
; #pragma unroll
;                     for (int r = 0; r < 16; ++r) o[d][r] *= f_; }
;         }
;         bcur = bnext; bnext = bnext + ABUF; if (bnext == 3 * ABUF) bnext = 0;
	s_nop 11
	v_max_f32_e32 v243, 0, v243
	v_exp_f32_e64 v244, -v243
	v_sub_f32_e32 v80, v80, v243
	v_sub_f32_e32 v81, v81, v243
	v_sub_f32_e32 v82, v82, v243
	v_sub_f32_e32 v83, v83, v243
	v_sub_f32_e32 v84, v84, v243
	v_sub_f32_e32 v85, v85, v243
	v_sub_f32_e32 v86, v86, v243
	v_sub_f32_e32 v87, v87, v243
	v_sub_f32_e32 v88, v88, v243
	v_sub_f32_e32 v89, v89, v243
	v_sub_f32_e32 v90, v90, v243
	v_sub_f32_e32 v91, v91, v243
	v_sub_f32_e32 v92, v92, v243
	v_sub_f32_e32 v93, v93, v243
	v_sub_f32_e32 v94, v94, v243
	v_sub_f32_e32 v95, v95, v243
	v_sub_f32_e32 v96, v96, v243
	v_sub_f32_e32 v97, v97, v243
	v_sub_f32_e32 v98, v98, v243
	v_sub_f32_e32 v99, v99, v243
	v_sub_f32_e32 v100, v100, v243
	v_sub_f32_e32 v101, v101, v243
	v_sub_f32_e32 v102, v102, v243
	v_sub_f32_e32 v103, v103, v243
	v_sub_f32_e32 v104, v104, v243
	v_sub_f32_e32 v105, v105, v243
	v_sub_f32_e32 v106, v106, v243
	v_sub_f32_e32 v107, v107, v243
	v_sub_f32_e32 v108, v108, v243
	v_sub_f32_e32 v109, v109, v243
	v_sub_f32_e32 v110, v110, v243
	v_sub_f32_e32 v111, v111, v243
	v_sub_f32_e32 v112, v112, v243
	v_sub_f32_e32 v113, v113, v243
	v_sub_f32_e32 v114, v114, v243
	v_sub_f32_e32 v115, v115, v243
	v_sub_f32_e32 v116, v116, v243
	v_sub_f32_e32 v117, v117, v243
	v_sub_f32_e32 v118, v118, v243
	v_sub_f32_e32 v119, v119, v243
	v_sub_f32_e32 v120, v120, v243
	v_sub_f32_e32 v121, v121, v243
	v_sub_f32_e32 v122, v122, v243
	v_sub_f32_e32 v123, v123, v243
	v_sub_f32_e32 v124, v124, v243
	v_sub_f32_e32 v125, v125, v243
	v_sub_f32_e32 v126, v126, v243
	v_sub_f32_e32 v127, v127, v243
	v_pk_mul_f32 v[64:65], v[64:65], v[244:245] op_sel_hi:[1,0]
	v_pk_mul_f32 v[66:67], v[66:67], v[244:245] op_sel_hi:[1,0]
	v_pk_mul_f32 v[68:69], v[68:69], v[244:245] op_sel_hi:[1,0]
	v_pk_mul_f32 v[70:71], v[70:71], v[244:245] op_sel_hi:[1,0]
	v_pk_mul_f32 v[72:73], v[72:73], v[244:245] op_sel_hi:[1,0]
	v_pk_mul_f32 v[74:75], v[74:75], v[244:245] op_sel_hi:[1,0]
	v_pk_mul_f32 v[76:77], v[76:77], v[244:245] op_sel_hi:[1,0]
	v_pk_mul_f32 v[78:79], v[78:79], v[244:245] op_sel_hi:[1,0]
	v_pk_mul_f32 v[48:49], v[48:49], v[244:245] op_sel_hi:[1,0]
	v_pk_mul_f32 v[50:51], v[50:51], v[244:245] op_sel_hi:[1,0]
	v_pk_mul_f32 v[52:53], v[52:53], v[244:245] op_sel_hi:[1,0]
	v_pk_mul_f32 v[54:55], v[54:55], v[244:245] op_sel_hi:[1,0]
	v_pk_mul_f32 v[56:57], v[56:57], v[244:245] op_sel_hi:[1,0]
	v_pk_mul_f32 v[58:59], v[58:59], v[244:245] op_sel_hi:[1,0]
	v_pk_mul_f32 v[60:61], v[60:61], v[244:245] op_sel_hi:[1,0]
	v_pk_mul_f32 v[62:63], v[62:63], v[244:245] op_sel_hi:[1,0]
	v_pk_mul_f32 v[32:33], v[32:33], v[244:245] op_sel_hi:[1,0]
	v_pk_mul_f32 v[34:35], v[34:35], v[244:245] op_sel_hi:[1,0]
	v_pk_mul_f32 v[36:37], v[36:37], v[244:245] op_sel_hi:[1,0]
	v_pk_mul_f32 v[38:39], v[38:39], v[244:245] op_sel_hi:[1,0]
	v_pk_mul_f32 v[40:41], v[40:41], v[244:245] op_sel_hi:[1,0]
	v_pk_mul_f32 v[42:43], v[42:43], v[244:245] op_sel_hi:[1,0]
	v_pk_mul_f32 v[44:45], v[44:45], v[244:245] op_sel_hi:[1,0]
	v_pk_mul_f32 v[46:47], v[46:47], v[244:245] op_sel_hi:[1,0]
	v_pk_mul_f32 v[16:17], v[16:17], v[244:245] op_sel_hi:[1,0]
	v_pk_mul_f32 v[18:19], v[18:19], v[244:245] op_sel_hi:[1,0]
	v_pk_mul_f32 v[20:21], v[20:21], v[244:245] op_sel_hi:[1,0]
	v_pk_mul_f32 v[22:23], v[22:23], v[244:245] op_sel_hi:[1,0]
	v_pk_mul_f32 v[24:25], v[24:25], v[244:245] op_sel_hi:[1,0]
	v_pk_mul_f32 v[26:27], v[26:27], v[244:245] op_sel_hi:[1,0]
	v_pk_mul_f32 v[28:29], v[28:29], v[244:245] op_sel_hi:[1,0]
	v_pk_mul_f32 v[30:31], v[30:31], v[244:245] op_sel_hi:[1,0]
	v_mul_f32_e32 v173, v173, v244
	v_mul_f32_e32 v202, v202, v244
	s_nop 1
.Latt2_e_noresc:
	s_waitcnt lgkmcnt(0)
	s_barrier
	s_cmpk_eq_i32 s31, 0xfc0
	s_cbranch_scc1 .Latt2_exit
	s_add_i32 s0, s27, s31
	s_add_i32 s30, s31, 64
	s_addk_i32 s0, 0xf021
	s_cmpk_gt_i32 s0, 0x7f
	s_cselect_b32 s0, 2, 1
	s_cmp_gt_i32 s30, s16
	s_cselect_b32 s29, s0, 0
	s_cmp_eq_u32 s29, s34
	s_cbranch_scc1 .Latt2_o_same
	s_cmp_eq_u32 s29, 2
	s_cselect_b32 s0, 1, 0
	s_lshl_b32 s0, s0, 10
	s_add_i32 s0, s0, 0x1f800
	s_cmp_eq_u32 s34, 2
	s_cselect_b32 s1, 1, 0
	s_lshl_b32 s1, s1, 10
	s_add_i32 s1, s1, 0x1f800
	v_mov_b32_e32 v238, s0
	v_mov_b32_e32 v239, s1
	ds_read_b32 v238, v238
	ds_read_b32 v239, v239
	s_cmp_eq_u32 s29, 1
	s_cselect_b32 s0, 0, 0x3f800000
	s_cmp_eq_u32 s34, 1
	s_cselect_b32 s1, 0, 0x3f800000
	s_waitcnt lgkmcnt(0)
	v_mul_f32_e32 v238, s0, v238
	v_mul_f32_e32 v239, s1, v239
	v_sub_f32_e32 v238, v238, v239
	v_add_f32_e32 v80, v80, v238
	v_add_f32_e32 v81, v81, v238
	v_add_f32_e32 v82, v82, v238
	v_add_f32_e32 v83, v83, v238
	v_add_f32_e32 v84, v84, v238
	v_add_f32_e32 v85, v85, v238
	v_add_f32_e32 v86, v86, v238
	v_add_f32_e32 v87, v87, v238
	v_add_f32_e32 v88, v88, v238
	v_add_f32_e32 v89, v89, v238
	v_add_f32_e32 v90, v90, v238
	v_add_f32_e32 v91, v91, v238
	v_add_f32_e32 v92, v92, v238
	v_add_f32_e32 v93, v93, v238
	v_add_f32_e32 v94, v94, v238
	v_add_f32_e32 v95, v95, v238
.Latt2_o_same:
	v_add_u32_e32 v203, s28, v164
	v_add_u32_e32 v235, s26, v176
	s_cmp_eq_u32 s29, 1
	s_cbranch_scc1 .Latt2_o_near
	ds_read_b128 v[178:181], v203
	ds_read_b128 v[182:185], v203 offset:4608
	ds_read_b128 v[186:189], v203 offset:32
	ds_read_b128 v[190:193], v203 offset:4640
	ds_read_b128 v[222:225], v203 offset:64
	ds_read_b128 v[226:229], v203 offset:4672
	ds_read_b128 v[230:233], v203 offset:96
	v_exp_f32_e32 v96, v96
	v_exp_f32_e32 v97, v97
	v_exp_f32_e32 v98, v98
	v_exp_f32_e32 v99, v99
	v_exp_f32_e32 v100, v100
	v_exp_f32_e32 v101, v101
	v_exp_f32_e32 v102, v102
	v_exp_f32_e32 v103, v103
	s_waitcnt lgkmcnt(6)
	v_mfma_f32_32x32x16_bf16 v[206:221], v[178:181], v[140:143], v[80:95]
	ds_read_b128 v[178:181], v203 offset:4704
	v_add_f32_e32 v173, v173, v96
	v_add_f32_e32 v202, v202, v97
	v_add_f32_e32 v173, v173, v98
	v_add_f32_e32 v202, v202, v99
	v_exp_f32_e32 v104, v104
	s_waitcnt lgkmcnt(6)
	v_mfma_f32_32x32x16_bf16 v[0:15], v[182:185], v[140:143], v[80:95]
	ds_read_b64_tr_b16 v[182:183], v235 offset:18432
	ds_read_b64_tr_b16 v[184:185], v235 offset:19968
	v_add_f32_e32 v173, v173, v100
	v_add_f32_e32 v202, v202, v101
	v_add_f32_e32 v173, v173, v102
	v_add_f32_e32 v202, v202, v103
	v_exp_f32_e32 v105, v105
	s_branch .Latt2_o_join
; #define LAS __attribute__((address_space(3)))
; #define A_VLOAD(dst, d) do { const LAS char* vb_ = vbase + ((d) >> 1) * AVS + ((d) & 1) * 64; \
;         _Pragma("unroll") for (int ks = 0; ks < 4; ++ks) { const s16x4 vl_ = vtr(vb_ + (16 * ks) * AVP), vh_ = vtr(vb_ + (16 * ks + 8) * AVP); \
;             dst[ks] = (bf16x8){vl_[0], vl_[1], vl_[2], vl_[3], vh_[0], vh_[1], vh_[2], vh_[3]}; } } while (0)
; __device__ __forceinline__ void attn_unit_A(const AttnP& P, int u, LAS char* lds) {
;     ...
;         const LAS char* vbase = lds + bcur + 2 * AKS + vrow * AVP + vcolb;
;     ...
;         bf16x8 vfa[4], vfb[4];
;         A_VLOAD(vfa, 0);
;         __builtin_amdgcn_sched_barrier(0);
;         float sacc = 0.f;
; #pragma unroll
;         for (int r = 0; r < 16; ++r) { sa0[r] = __builtin_amdgcn_exp2f(sa0[r]); sa1[r] = __builtin_amdgcn_exp2f(sa1[r]); sacc += sa0[r] + sa1[r]; }
.Latt2_o_near:
	v_add_u32_e32 v238, s31, v177
	s_add_i32 s0, 0, 0x1f800
	v_add_u32_e32 v206, 0xfffff040, v238
	v_med3_i32 v206, v206, s87, v240
	v_lshl_add_u32 v206, v206, 2, s0
	v_add_u32_e32 v207, 0xfffff041, v238
	v_med3_i32 v207, v207, s87, v240
	v_lshl_add_u32 v207, v207, 2, s0
	v_add_u32_e32 v208, 0xfffff042, v238
	v_med3_i32 v208, v208, s87, v240
	v_lshl_add_u32 v208, v208, 2, s0
	v_add_u32_e32 v209, 0xfffff043, v238
	v_med3_i32 v209, v209, s87, v240
	v_lshl_add_u32 v209, v209, 2, s0
	v_add_u32_e32 v210, 0xfffff048, v238
	v_med3_i32 v210, v210, s87, v240
	v_lshl_add_u32 v210, v210, 2, s0
	v_add_u32_e32 v211, 0xfffff049, v238
	v_med3_i32 v211, v211, s87, v240
	v_lshl_add_u32 v211, v211, 2, s0
	v_add_u32_e32 v212, 0xfffff04a, v238
	v_med3_i32 v212, v212, s87, v240
	v_lshl_add_u32 v212, v212, 2, s0
	v_add_u32_e32 v213, 0xfffff04b, v238
	v_med3_i32 v213, v213, s87, v240
	v_lshl_add_u32 v213, v213, 2, s0
	v_add_u32_e32 v214, 0xfffff050, v238
	v_med3_i32 v214, v214, s87, v240
	v_lshl_add_u32 v214, v214, 2, s0
	v_add_u32_e32 v215, 0xfffff051, v238
	v_med3_i32 v215, v215, s87, v240
	v_lshl_add_u32 v215, v215, 2, s0
	v_add_u32_e32 v216, 0xfffff052, v238
	v_med3_i32 v216, v216, s87, v240
	v_lshl_add_u32 v216, v216, 2, s0
	v_add_u32_e32 v217, 0xfffff053, v238
	v_med3_i32 v217, v217, s87, v240
	v_lshl_add_u32 v217, v217, 2, s0
	v_add_u32_e32 v218, 0xfffff058, v238
	v_med3_i32 v218, v218, s87, v240
	v_lshl_add_u32 v218, v218, 2, s0
	v_add_u32_e32 v219, 0xfffff059, v238
	v_med3_i32 v219, v219, s87, v240
	v_lshl_add_u32 v219, v219, 2, s0
	v_add_u32_e32 v220, 0xfffff05a, v238
	v_med3_i32 v220, v220, s87, v240
	v_lshl_add_u32 v220, v220, 2, s0
	v_add_u32_e32 v221, 0xfffff05b, v238
	v_med3_i32 v221, v221, s87, v240
	v_lshl_add_u32 v221, v221, 2, s0
	ds_read_b32 v206, v206 offset:512
	ds_read_b32 v207, v207 offset:512
	ds_read_b32 v208, v208 offset:512
	ds_read_b32 v209, v209 offset:512
	ds_read_b32 v210, v210 offset:512
	ds_read_b32 v211, v211 offset:512
	ds_read_b32 v212, v212 offset:512
	ds_read_b32 v213, v213 offset:512
	ds_read_b32 v214, v214 offset:512
	ds_read_b32 v215, v215 offset:512
	ds_read_b32 v216, v216 offset:512
	ds_read_b32 v217, v217 offset:512
	ds_read_b32 v218, v218 offset:512
	ds_read_b32 v219, v219 offset:512
	ds_read_b32 v220, v220 offset:512
	ds_read_b32 v221, v221 offset:512
	v_add_u32_e32 v0, 0xfffff060, v238
	v_med3_i32 v0, v0, s87, v240
	v_lshl_add_u32 v0, v0, 2, s0
	v_add_u32_e32 v1, 0xfffff061, v238
	v_med3_i32 v1, v1, s87, v240
	v_lshl_add_u32 v1, v1, 2, s0
	v_add_u32_e32 v2, 0xfffff062, v238
	v_med3_i32 v2, v2, s87, v240
	v_lshl_add_u32 v2, v2, 2, s0
	v_add_u32_e32 v3, 0xfffff063, v238
	v_med3_i32 v3, v3, s87, v240
	v_lshl_add_u32 v3, v3, 2, s0
	v_add_u32_e32 v4, 0xfffff068, v238
	v_med3_i32 v4, v4, s87, v240
	v_lshl_add_u32 v4, v4, 2, s0
	v_add_u32_e32 v5, 0xfffff069, v238
	v_med3_i32 v5, v5, s87, v240
	v_lshl_add_u32 v5, v5, 2, s0
	v_add_u32_e32 v6, 0xfffff06a, v238
	v_med3_i32 v6, v6, s87, v240
	v_lshl_add_u32 v6, v6, 2, s0
	v_add_u32_e32 v7, 0xfffff06b, v238
	v_med3_i32 v7, v7, s87, v240
	v_lshl_add_u32 v7, v7, 2, s0
	v_add_u32_e32 v8, 0xfffff070, v238
	v_med3_i32 v8, v8, s87, v240
	v_lshl_add_u32 v8, v8, 2, s0
	v_add_u32_e32 v9, 0xfffff071, v238
	v_med3_i32 v9, v9, s87, v240
	v_lshl_add_u32 v9, v9, 2, s0
	v_add_u32_e32 v10, 0xfffff072, v238
	v_med3_i32 v10, v10, s87, v240
	v_lshl_add_u32 v10, v10, 2, s0
	v_add_u32_e32 v11, 0xfffff073, v238
	v_med3_i32 v11, v11, s87, v240
	v_lshl_add_u32 v11, v11, 2, s0
	v_add_u32_e32 v12, 0xfffff078, v238
	v_med3_i32 v12, v12, s87, v240
	v_lshl_add_u32 v12, v12, 2, s0
	v_add_u32_e32 v13, 0xfffff079, v238
	v_med3_i32 v13, v13, s87, v240
	v_lshl_add_u32 v13, v13, 2, s0
	v_add_u32_e32 v14, 0xfffff07a, v238
	v_med3_i32 v14, v14, s87, v240
	v_lshl_add_u32 v14, v14, 2, s0
	v_add_u32_e32 v15, 0xfffff07b, v238
	v_med3_i32 v15, v15, s87, v240
	v_lshl_add_u32 v15, v15, 2, s0
	ds_read_b32 v0, v0 offset:512
	ds_read_b32 v1, v1 offset:512
	ds_read_b32 v2, v2 offset:512
	ds_read_b32 v3, v3 offset:512
	ds_read_b32 v4, v4 offset:512
	ds_read_b32 v5, v5 offset:512
	ds_read_b32 v6, v6 offset:512
	ds_read_b32 v7, v7 offset:512
	ds_read_b32 v8, v8 offset:512
	ds_read_b32 v9, v9 offset:512
	ds_read_b32 v10, v10 offset:512
	ds_read_b32 v11, v11 offset:512
	ds_read_b32 v12, v12 offset:512
	ds_read_b32 v13, v13 offset:512
	ds_read_b32 v14, v14 offset:512
	ds_read_b32 v15, v15 offset:512
	s_waitcnt lgkmcnt(0)
	v_add_f32_e32 v206, v206, v80
	v_add_f32_e32 v207, v207, v80
	v_add_f32_e32 v208, v208, v80
	v_add_f32_e32 v209, v209, v80
	v_add_f32_e32 v210, v210, v80
	v_add_f32_e32 v211, v211, v80
	v_add_f32_e32 v212, v212, v80
	v_add_f32_e32 v213, v213, v80
	v_add_f32_e32 v214, v214, v80
	v_add_f32_e32 v215, v215, v80
	v_add_f32_e32 v216, v216, v80
	v_add_f32_e32 v217, v217, v80
	v_add_f32_e32 v218, v218, v80
	v_add_f32_e32 v219, v219, v80
	v_add_f32_e32 v220, v220, v80
	v_add_f32_e32 v221, v221, v80
	v_add_f32_e32 v0, v0, v80
	v_add_f32_e32 v1, v1, v80
	v_add_f32_e32 v2, v2, v80
	v_add_f32_e32 v3, v3, v80
	v_add_f32_e32 v4, v4, v80
	v_add_f32_e32 v5, v5, v80
	v_add_f32_e32 v6, v6, v80
	v_add_f32_e32 v7, v7, v80
	v_add_f32_e32 v8, v8, v80
	v_add_f32_e32 v9, v9, v80
	v_add_f32_e32 v10, v10, v80
	v_add_f32_e32 v11, v11, v80
	v_add_f32_e32 v12, v12, v80
	v_add_f32_e32 v13, v13, v80
	v_add_f32_e32 v14, v14, v80
	v_add_f32_e32 v15, v15, v80
	ds_read_b128 v[178:181], v203
	ds_read_b128 v[182:185], v203 offset:4608
	ds_read_b128 v[186:189], v203 offset:32
	ds_read_b128 v[190:193], v203 offset:4640
	ds_read_b128 v[222:225], v203 offset:64
	ds_read_b128 v[226:229], v203 offset:4672
	ds_read_b128 v[230:233], v203 offset:96
	v_exp_f32_e32 v96, v96
	v_exp_f32_e32 v97, v97
	v_exp_f32_e32 v98, v98
	v_exp_f32_e32 v99, v99
	v_exp_f32_e32 v100, v100
	v_exp_f32_e32 v101, v101
	v_exp_f32_e32 v102, v102
	v_exp_f32_e32 v103, v103
	s_waitcnt lgkmcnt(6)
	v_mfma_f32_32x32x16_bf16 v[206:221], v[178:181], v[140:143], v[206:221]
	ds_read_b128 v[178:181], v203 offset:4704
	v_add_f32_e32 v173, v173, v96
	v_add_f32_e32 v202, v202, v97
	v_add_f32_e32 v173, v173, v98
	v_add_f32_e32 v202, v202, v99
	v_exp_f32_e32 v104, v104
	s_waitcnt lgkmcnt(6)
	v_mfma_f32_32x32x16_bf16 v[0:15], v[182:185], v[140:143], v[0:15]
	ds_read_b64_tr_b16 v[182:183], v235 offset:18432
	ds_read_b64_tr_b16 v[184:185], v235 offset:19968
	v_add_f32_e32 v173, v173, v100
	v_add_f32_e32 v202, v202, v101
	v_add_f32_e32 v173, v173, v102
	v_add_f32_e32 v202, v202, v103
	v_exp_f32_e32 v105, v105
; __device__ __forceinline__ void attn_unit_A(const AttnP& P, int u, LAS char* lds) {
;     ...
;         if (more) { A_WRITE(bnext); if (t + 2 < nt) A_ISSUE(t + 2); }
;         int clsn = clsk;
;         if (more) { clsn = A_CLS(t + 1);
;             if (clsn != clsk) { const float dc = A_CVAL(clsn) - A_CVAL(clsk); clsk = clsn;
; #pragma unroll
;                 for (int r = 0; r < 16; ++r) negc[r] += dc; } }
;     ...
;         const LAS char* vbase = lds + bcur + 2 * AKS + vrow * AVP + vcolb;
;     ...
;         bf16x8 vfa[4], vfb[4];
;         A_VLOAD(vfa, 0);
;         __builtin_amdgcn_sched_barrier(0);
;         float sacc = 0.f;
; #pragma unroll
;         for (int r = 0; r < 16; ++r) { sa0[r] = __builtin_amdgcn_exp2f(sa0[r]); sa1[r] = __builtin_amdgcn_exp2f(sa1[r]); sacc += sa0[r] + sa1[r]; }
;         lrun += sacc;
;         bf16x8 pf[4];
;         { u32x4 a;
;           a.x = cvtpk(sa0[0], sa0[1]); a.y = cvtpk(sa0[2], sa0[3]); a.z = cvtpk(sa0[4], sa0[5]); a.w = cvtpk(sa0[6], sa0[7]); pf[0] = __builtin_bit_cast(bf16x8, a);
;           a.x = cvtpk(sa0[8], sa0[9]); a.y = cvtpk(sa0[10], sa0[11]); a.z = cvtpk(sa0[12], sa0[13]); a.w = cvtpk(sa0[14], sa0[15]); pf[1] = __builtin_bit_cast(bf16x8, a);
;           a.x = cvtpk(sa1[0], sa1[1]); a.y = cvtpk(sa1[2], sa1[3]); a.z = cvtpk(sa1[4], sa1[5]); a.w = cvtpk(sa1[6], sa1[7]); pf[2] = __builtin_bit_cast(bf16x8, a);
;           a.x = cvtpk(sa1[8], sa1[9]); a.y = cvtpk(sa1[10], sa1[11]); a.z = cvtpk(sa1[12], sa1[13]); a.w = cvtpk(sa1[14], sa1[15]); pf[3] = __builtin_bit_cast(bf16x8, a); }
;         __builtin_amdgcn_sched_barrier(0);
;         A_VLOAD(vfb, 1);
;         __builtin_amdgcn_sched_barrier(0);
;         A_VMMA(vfa, 0);
;         A_VLOAD(vfa, 2);
;         __builtin_amdgcn_sched_barrier(0);
;         A_VMMA(vfb, 1);
;         A_VLOAD(vfb, 3);
;         __builtin_amdgcn_sched_barrier(0);
;         A_VMMA(vfa, 2);
;         __builtin_amdgcn_sched_barrier(0);
;         A_VMMA(vfb, 3);
;     ...
;         __builtin_amdgcn_sched_barrier(0); A_BAR(); A_QKBLK();
;     ...
;         if (more) {
;             if (clsn == 1) A_NEAR(sa0, sa1, t + 1);
;             float mx_; A_ROWMAX(sa0, sa1, mx_);
;             if (__any(mx_ > 8.0f)) { const float dl = fmaxf(mx_, 0.f); const float f_ = __builtin_amdgcn_exp2f(-dl); lrun *= f_;
; #pragma unroll
;                 for (int r = 0; r < 16; ++r) { sa0[r] -= dl; sa1[r] -= dl; negc[r] -= dl; }
; #pragma unroll
.Latt2_o_join:
	s_waitcnt lgkmcnt(7)
	v_mfma_f32_32x32x16_bf16 v[206:221], v[186:189], v[136:139], v[206:221]
	ds_read_b64_tr_b16 v[186:187], v235 offset:18496
	ds_read_b64_tr_b16 v[188:189], v235 offset:20032
	v_cvt_pk_bf16_f32 v96, v96, v97
	v_cvt_pk_bf16_f32 v97, v98, v99
	v_cvt_pk_bf16_f32 v98, v100, v101
	v_cvt_pk_bf16_f32 v99, v102, v103
	v_exp_f32_e32 v106, v106
	s_waitcnt lgkmcnt(8)
	v_mfma_f32_32x32x16_bf16 v[0:15], v[190:193], v[136:139], v[0:15]
	ds_read_b64_tr_b16 v[190:191], v235 offset:30720
	ds_read_b64_tr_b16 v[192:193], v235 offset:32256
	v_exp_f32_e32 v107, v107
	v_exp_f32_e32 v108, v108
	v_exp_f32_e32 v109, v109
	s_waitcnt lgkmcnt(9)
	v_mfma_f32_32x32x16_bf16 v[206:221], v[222:225], v[132:135], v[206:221]
	ds_read_b64_tr_b16 v[222:223], v235 offset:30784
	ds_read_b64_tr_b16 v[224:225], v235 offset:32320
	v_exp_f32_e32 v110, v110
	v_exp_f32_e32 v111, v111
	v_add_f32_e32 v173, v173, v104
	v_add_f32_e32 v202, v202, v105
	s_waitcnt lgkmcnt(10)
	v_mfma_f32_32x32x16_bf16 v[0:15], v[226:229], v[132:135], v[0:15]
	ds_read_b64_tr_b16 v[226:227], v235 offset:21504
	ds_read_b64_tr_b16 v[228:229], v235 offset:23040
	v_add_f32_e32 v173, v173, v106
	v_add_f32_e32 v202, v202, v107
	v_add_f32_e32 v173, v173, v108
	v_add_f32_e32 v202, v202, v109
	v_add_f32_e32 v173, v173, v110
	v_add_f32_e32 v202, v202, v111
	s_waitcnt lgkmcnt(11)
	v_mfma_f32_32x32x16_bf16 v[206:221], v[230:233], v[128:131], v[206:221]
	ds_read_b64_tr_b16 v[230:231], v235 offset:21568
	ds_read_b64_tr_b16 v[232:233], v235 offset:23104
	v_cvt_pk_bf16_f32 v100, v104, v105
	v_cvt_pk_bf16_f32 v101, v106, v107
	v_cvt_pk_bf16_f32 v102, v108, v109
	v_cvt_pk_bf16_f32 v103, v110, v111
	v_exp_f32_e32 v112, v112
	s_waitcnt lgkmcnt(12)
	v_mfma_f32_32x32x16_bf16 v[0:15], v[178:181], v[128:131], v[0:15]
	ds_read_b64_tr_b16 v[178:179], v235 offset:33792
	ds_read_b64_tr_b16 v[180:181], v235 offset:35328
	v_exp_f32_e32 v113, v113
	v_exp_f32_e32 v114, v114
	v_exp_f32_e32 v115, v115
	s_waitcnt lgkmcnt(12)
	v_mfma_f32_32x32x16_bf16 v[64:79], v[182:185], v[96:99], v[64:79]
	ds_read_b64_tr_b16 v[182:183], v235 offset:33856
	ds_read_b64_tr_b16 v[184:185], v235 offset:35392
	v_exp_f32_e32 v116, v116
	v_exp_f32_e32 v117, v117
	v_exp_f32_e32 v118, v118
	s_waitcnt lgkmcnt(12)
	v_mfma_f32_32x32x16_bf16 v[48:63], v[186:189], v[96:99], v[48:63]
	ds_read_b64_tr_b16 v[186:187], v235 offset:24576
	ds_read_b64_tr_b16 v[188:189], v235 offset:26112
	v_exp_f32_e32 v119, v119
	v_add_f32_e32 v173, v173, v112
	v_add_f32_e32 v202, v202, v113
	v_add_f32_e32 v173, v173, v114
	v_add_f32_e32 v202, v202, v115
	s_waitcnt lgkmcnt(12)
	v_mfma_f32_32x32x16_bf16 v[32:47], v[190:193], v[96:99], v[32:47]
	ds_read_b64_tr_b16 v[190:191], v235 offset:24640
	ds_read_b64_tr_b16 v[192:193], v235 offset:26176
	v_add_f32_e32 v173, v173, v116
	v_add_f32_e32 v202, v202, v117
	v_add_f32_e32 v173, v173, v118
	v_add_f32_e32 v202, v202, v119
	v_exp_f32_e32 v120, v120
	s_waitcnt lgkmcnt(12)
	v_mfma_f32_32x32x16_bf16 v[16:31], v[222:225], v[96:99], v[16:31]
	ds_read_b64_tr_b16 v[222:223], v235 offset:36864
	ds_read_b64_tr_b16 v[224:225], v235 offset:38400
	v_cvt_pk_bf16_f32 v104, v112, v113
	v_cvt_pk_bf16_f32 v105, v114, v115
	v_cvt_pk_bf16_f32 v106, v116, v117
	v_cvt_pk_bf16_f32 v107, v118, v119
	v_exp_f32_e32 v121, v121
	s_waitcnt lgkmcnt(12)
	v_mfma_f32_32x32x16_bf16 v[64:79], v[226:229], v[100:103], v[64:79]
	ds_read_b64_tr_b16 v[226:227], v235 offset:36928
	ds_read_b64_tr_b16 v[228:229], v235 offset:38464
	v_exp_f32_e32 v122, v122
	v_exp_f32_e32 v123, v123
	v_exp_f32_e32 v124, v124
	s_waitcnt lgkmcnt(12)
	v_mfma_f32_32x32x16_bf16 v[48:63], v[230:233], v[100:103], v[48:63]
	ds_read_b64_tr_b16 v[230:231], v235 offset:27648
	ds_read_b64_tr_b16 v[232:233], v235 offset:29184
	v_exp_f32_e32 v125, v125
	v_exp_f32_e32 v126, v126
	v_exp_f32_e32 v127, v127
	s_waitcnt lgkmcnt(12)
	v_mfma_f32_32x32x16_bf16 v[32:47], v[178:181], v[100:103], v[32:47]
	ds_read_b64_tr_b16 v[178:179], v235 offset:27712
	ds_read_b64_tr_b16 v[180:181], v235 offset:29248
	v_add_f32_e32 v173, v173, v120
	v_add_f32_e32 v202, v202, v121
	v_add_f32_e32 v173, v173, v122
	v_add_f32_e32 v202, v202, v123
	v_add_f32_e32 v173, v173, v124
	v_add_f32_e32 v202, v202, v125
	s_waitcnt lgkmcnt(12)
	v_mfma_f32_32x32x16_bf16 v[16:31], v[182:185], v[100:103], v[16:31]
	ds_read_b64_tr_b16 v[182:183], v235 offset:39936
	ds_read_b64_tr_b16 v[184:185], v235 offset:41472
	v_add_f32_e32 v173, v173, v126
	v_add_f32_e32 v202, v202, v127
	v_cvt_pk_bf16_f32 v108, v120, v121
	v_cvt_pk_bf16_f32 v109, v122, v123
	v_cvt_pk_bf16_f32 v110, v124, v125
	v_cvt_pk_bf16_f32 v111, v126, v127
	s_waitcnt lgkmcnt(12)
	v_mfma_f32_32x32x16_bf16 v[64:79], v[186:189], v[104:107], v[64:79]
	ds_read_b64_tr_b16 v[186:187], v235 offset:40000
	ds_read_b64_tr_b16 v[188:189], v235 offset:41536
	v_max3_f32 v243, v206, v207, v208
	v_max3_f32 v239, v0, v1, v2
	v_max3_f32 v243, v243, v209, v210
	v_max3_f32 v239, v239, v3, v4
	v_max3_f32 v243, v243, v211, v212
	s_waitcnt lgkmcnt(12)
	v_mfma_f32_32x32x16_bf16 v[48:63], v[190:193], v[104:107], v[48:63]
	v_max3_f32 v239, v239, v5, v6
	v_max3_f32 v243, v243, v213, v214
	v_max3_f32 v239, v239, v7, v8
	v_max3_f32 v243, v243, v215, v216
	v_max3_f32 v239, v239, v9, v10
	v_max3_f32 v243, v243, v217, v218
	s_waitcnt lgkmcnt(10)
	v_mfma_f32_32x32x16_bf16 v[32:47], v[222:225], v[104:107], v[32:47]
	v_max3_f32 v239, v239, v11, v12
	v_max3_f32 v243, v243, v219, v220
	v_max3_f32 v239, v239, v13, v14
	v_max_f32_e32 v243, v243, v221
	v_max_f32_e32 v239, v239, v15
	v_max_f32_e32 v243, v243, v239
	s_waitcnt lgkmcnt(8)
	v_mfma_f32_32x32x16_bf16 v[16:31], v[226:229], v[104:107], v[16:31]
	s_waitcnt vmcnt(0)
	v_add3_u32 v238, s35, v172, v160
	v_add3_u32 v239, s35, v174, v160
	ds_write_b128 v238, v[156:159]
	ds_write_b128 v238, v[152:155] offset:9216
	s_waitcnt lgkmcnt(8)
	v_mfma_f32_32x32x16_bf16 v[64:79], v[230:233], v[108:111], v[64:79]
	ds_write_b128 v239, v[148:151] offset:18432
	ds_write_b128 v239, v[144:147] offset:30720
	v_mov_b32_e32 v239, v243
	s_min_i32 s0, s30, 0xf80
	v_add_u32_e32 v238, s0, v175
	v_min_i32_e32 v238, 0x100f, v238
	s_waitcnt lgkmcnt(8)
	v_mfma_f32_32x32x16_bf16 v[48:63], v[178:181], v[108:111], v[48:63]
	v_permlane32_swap_b32_e32 v243, v239
	v_mad_i64_i32 v[244:245], s[0:1], v238, s51, v[162:163]
	global_load_dwordx4 v[156:159], v[244:245], off offset:1024
	global_load_dwordx4 v[152:155], v[244:245], off offset:1152
	s_waitcnt lgkmcnt(6)
	v_mfma_f32_32x32x16_bf16 v[32:47], v[182:185], v[108:111], v[32:47]
	global_load_dwordx4 v[148:151], v[244:245], off offset:2048
	global_load_dwordx4 v[144:147], v[244:245], off offset:2176
	v_max_f32_e32 v243, v243, v239
	s_waitcnt lgkmcnt(4)
	v_mfma_f32_32x32x16_bf16 v[16:31], v[186:189], v[108:111], v[16:31]
	s_mov_b32 s34, s29
	s_mov_b32 s26, s28
	s_mov_b32 s28, s35
	s_add_i32 s0, s35, 0xa800
	s_cmp_lg_u32 s0, 0x1f800
	s_cselect_b32 s35, s0, 0
	s_mov_b32 s31, s30
	v_cmp_lt_f32_e32 vcc, s10, v243
	s_cbranch_vccz .Latt2_o_noresc
; __device__ __forceinline__ void attn_unit_A(const AttnP& P, int u, LAS char* lds) {
;     ...
;             float mx_; A_ROWMAX(sa0, sa1, mx_);
;             if (__any(mx_ > 8.0f)) { const float dl = fmaxf(mx_, 0.f); const float f_ = __builtin_amdgcn_exp2f(-dl); lrun *= f_;
; #pragma unroll
;                 for (int r = 0; r < 16; ++r) { sa0[r] -= dl; sa1[r] -= dl; negc[r] -= dl; }
; #pragma unroll
;                 for (int d = 0; d < 4; ++d)
; #pragma unroll
;                     for (int r = 0; r < 16; ++r) o[d][r] *= f_; }
	s_nop 11
	v_max_f32_e32 v243, 0, v243
	v_exp_f32_e64 v244, -v243
	v_sub_f32_e32 v80, v80, v243
	v_sub_f32_e32 v81, v81, v243
	v_sub_f32_e32 v82, v82, v243
	v_sub_f32_e32 v83, v83, v243
	v_sub_f32_e32 v84, v84, v243
	v_sub_f32_e32 v85, v85, v243
	v_sub_f32_e32 v86, v86, v243
	v_sub_f32_e32 v87, v87, v243
	v_sub_f32_e32 v88, v88, v243
	v_sub_f32_e32 v89, v89, v243
	v_sub_f32_e32 v90, v90, v243
	v_sub_f32_e32 v91, v91, v243
	v_sub_f32_e32 v92, v92, v243
	v_sub_f32_e32 v93, v93, v243
	v_sub_f32_e32 v94, v94, v243
	v_sub_f32_e32 v95, v95, v243
	v_sub_f32_e32 v206, v206, v243
	v_sub_f32_e32 v207, v207, v243
	v_sub_f32_e32 v208, v208, v243
	v_sub_f32_e32 v209, v209, v243
	v_sub_f32_e32 v210, v210, v243
	v_sub_f32_e32 v211, v211, v243
	v_sub_f32_e32 v212, v212, v243
	v_sub_f32_e32 v213, v213, v243
	v_sub_f32_e32 v214, v214, v243
	v_sub_f32_e32 v215, v215, v243
	v_sub_f32_e32 v216, v216, v243
	v_sub_f32_e32 v217, v217, v243
	v_sub_f32_e32 v218, v218, v243
	v_sub_f32_e32 v219, v219, v243
	v_sub_f32_e32 v220, v220, v243
	v_sub_f32_e32 v221, v221, v243
	v_sub_f32_e32 v0, v0, v243
	v_sub_f32_e32 v1, v1, v243
	v_sub_f32_e32 v2, v2, v243
	v_sub_f32_e32 v3, v3, v243
	v_sub_f32_e32 v4, v4, v243
	v_sub_f32_e32 v5, v5, v243
	v_sub_f32_e32 v6, v6, v243
	v_sub_f32_e32 v7, v7, v243
	v_sub_f32_e32 v8, v8, v243
	v_sub_f32_e32 v9, v9, v243
	v_sub_f32_e32 v10, v10, v243
	v_sub_f32_e32 v11, v11, v243
	v_sub_f32_e32 v12, v12, v243
	v_sub_f32_e32 v13, v13, v243
	v_sub_f32_e32 v14, v14, v243
	v_sub_f32_e32 v15, v15, v243
	v_pk_mul_f32 v[64:65], v[64:65], v[244:245] op_sel_hi:[1,0]
	v_pk_mul_f32 v[66:67], v[66:67], v[244:245] op_sel_hi:[1,0]
	v_pk_mul_f32 v[68:69], v[68:69], v[244:245] op_sel_hi:[1,0]
	v_pk_mul_f32 v[70:71], v[70:71], v[244:245] op_sel_hi:[1,0]
	v_pk_mul_f32 v[72:73], v[72:73], v[244:245] op_sel_hi:[1,0]
	v_pk_mul_f32 v[74:75], v[74:75], v[244:245] op_sel_hi:[1,0]
	v_pk_mul_f32 v[76:77], v[76:77], v[244:245] op_sel_hi:[1,0]
	v_pk_mul_f32 v[78:79], v[78:79], v[244:245] op_sel_hi:[1,0]
	v_pk_mul_f32 v[48:49], v[48:49], v[244:245] op_sel_hi:[1,0]
	v_pk_mul_f32 v[50:51], v[50:51], v[244:245] op_sel_hi:[1,0]
	v_pk_mul_f32 v[52:53], v[52:53], v[244:245] op_sel_hi:[1,0]
	v_pk_mul_f32 v[54:55], v[54:55], v[244:245] op_sel_hi:[1,0]
	v_pk_mul_f32 v[56:57], v[56:57], v[244:245] op_sel_hi:[1,0]
	v_pk_mul_f32 v[58:59], v[58:59], v[244:245] op_sel_hi:[1,0]
	v_pk_mul_f32 v[60:61], v[60:61], v[244:245] op_sel_hi:[1,0]
	v_pk_mul_f32 v[62:63], v[62:63], v[244:245] op_sel_hi:[1,0]
	v_pk_mul_f32 v[32:33], v[32:33], v[244:245] op_sel_hi:[1,0]
	v_pk_mul_f32 v[34:35], v[34:35], v[244:245] op_sel_hi:[1,0]
	v_pk_mul_f32 v[36:37], v[36:37], v[244:245] op_sel_hi:[1,0]
	v_pk_mul_f32 v[38:39], v[38:39], v[244:245] op_sel_hi:[1,0]
	v_pk_mul_f32 v[40:41], v[40:41], v[244:245] op_sel_hi:[1,0]
	v_pk_mul_f32 v[42:43], v[42:43], v[244:245] op_sel_hi:[1,0]
	v_pk_mul_f32 v[44:45], v[44:45], v[244:245] op_sel_hi:[1,0]
	v_pk_mul_f32 v[46:47], v[46:47], v[244:245] op_sel_hi:[1,0]
	v_pk_mul_f32 v[16:17], v[16:17], v[244:245] op_sel_hi:[1,0]
	v_pk_mul_f32 v[18:19], v[18:19], v[244:245] op_sel_hi:[1,0]
	v_pk_mul_f32 v[20:21], v[20:21], v[244:245] op_sel_hi:[1,0]
	v_pk_mul_f32 v[22:23], v[22:23], v[244:245] op_sel_hi:[1,0]
	v_pk_mul_f32 v[24:25], v[24:25], v[244:245] op_sel_hi:[1,0]
	v_pk_mul_f32 v[26:27], v[26:27], v[244:245] op_sel_hi:[1,0]
	v_pk_mul_f32 v[28:29], v[28:29], v[244:245] op_sel_hi:[1,0]
	v_pk_mul_f32 v[30:31], v[30:31], v[244:245] op_sel_hi:[1,0]
	v_mul_f32_e32 v173, v173, v244
	v_mul_f32_e32 v202, v202, v244
	s_nop 1

; __device__ __forceinline__ void attn_unit_A(const AttnP& P, int u, LAS char* lds) {
;     ...
;     const float inv = 1.0f / (lrun + __shfl_xor(lrun, 32));
.Latt2_exit:
	v_add_f32_e32 v173, v173, v202
	v_mov_b32_e32 v1, 0
	s_mov_b32 s15, s26
	s_mov_b32 s35, s28
	s_mov_b32 s29, s34
	s_nop 3

; #define LAS __attribute__((address_space(3)))
; template <int MODE> __device__ __forceinline__ void attn_unit(const AttnP& P, int u, LAS char* lds, bool fill) {
;     ...
;     for (int t = 0; t < nt; ++t) {
;         __syncthreads();
; #pragma unroll
;         for (int s = 0; s < NS; ++s) *(LAS u32x4*)(lds + s * ASLOT + lrow * APITCH + lch * 16) = pre[s];
;         __syncthreads();
;         if (t + 1 < nt) ISSUE(t + 1);
;         const int tok0 = TILE_TOK0(t);
;         f32x16 p0, p1;
; #pragma unroll
;         for (int r = 0; r < 16; ++r) { p0[r] = 0.f; p1[r] = 0.f; }
; #pragma unroll
;         for (int ds = 0; ds < 4; ++ds) {
;             const bf16x8 k0 = *(const LAS bf16x8*)(kb + ds * 32);
;             const bf16x8 k1 = *(const LAS bf16x8*)(kb + 32 * APITCH + ds * 32);
;             p0 = __builtin_amdgcn_mfma_f32_32x32x16_bf16(k0, qr[ds], p0, 0, 0, 0);
;             p1 = __builtin_amdgcn_mfma_f32_32x32x16_bf16(k1, qr[ds], p1, 0, 0, 0);
;         }
;         if (MODE == 0) {
;             const bool farl = (tok0 + 63 + 128 <= qtok0), farr = (tok0 - (qtok0 + 31) >= 128) && (tok0 + 64 <= LT);
;             if (farl || farr) { const float cb = farl ? mytab[0] : mytab[256];
; #pragma unroll
;                 for (int r = 0; r < 16; ++r) { p0[r] += cb; p1[r] += cb; } }
;             else {
; #pragma unroll
;                 for (int r = 0; r < 16; ++r) { const int tk0 = tok0 + crow(r, hi), tk1 = tk0 + 32;
;                     int i0 = tk0 - tq + 128; i0 = i0 < 0 ? 0 : (i0 > 256 ? 256 : i0); int i1 = tk1 - tq + 128; i1 = i1 < 0 ? 0 : (i1 > 256 ? 256 : i1);
;                     p0[r] = tk0 < LT ? p0[r] + mytab[i0] : NEGV; p1[r] = tk1 < LT ? p1[r] + mytab[i1] : NEGV; } }
;         } else if (MODE == 2) {
;           if (tok0 >= NMETA && tok0 + 64 <= LT) {
;             const LAS float* t2 = mytab2 + (tok0 - tq + 191 + 4 * hi);
; #pragma unroll
;             for (int r = 0; r < 16; ++r) { p0[r] += t2[(r & 3) + 8 * (r >> 2)]; p1[r] += t2[(r & 3) + 8 * (r >> 2) + 32]; }
;           } else
; #pragma unroll
;             for (int r = 0; r < 16; ++r) { const int tk0 = tok0 + crow(r, hi), tk1 = tk0 + 32; const int r0 = tk0 - tq, r1 = tk1 - tq;
;                 int i0 = r0 + 128; i0 = i0 < 0 ? 0 : (i0 > 256 ? 256 : i0); int i1 = r1 + 128; i1 = i1 < 0 ? 0 : (i1 > 256 ? 256 : i1);
.LBB0_1079:
	s_add_i32 s38, s38, 1
	s_waitcnt lgkmcnt(0)
	s_barrier
	s_waitcnt vmcnt(1)
	ds_write_b128 v0, v[118:121]
	s_waitcnt vmcnt(0)
	ds_write_b128 v0, v[114:117] offset:9216
	s_waitcnt lgkmcnt(0)
	s_barrier
	s_cmp_ge_i32 s38, s30
	s_cbranch_scc1 .Lgqa1_noload
	s_add_i32 s15, s34, 0x80
	s_add_i32 s16, s14, s34
	s_and_b64 s[0:1], s[46:47], exec
	s_cselect_b32 s0, s16, s15
	v_add_u32_e32 v34, s0, v126
	v_min_i32_e32 v34, 0x100f, v34
	v_mad_i64_i32 v[34:35], s[0:1], v34, s51, v[122:123]
	v_lshl_add_u64 v[36:37], v[34:35], 0, s[80:81]
	s_mov_b32 s59, s81
	v_lshl_add_u64 v[34:35], v[34:35], 0, s[58:59]
	global_load_dwordx4 v[118:121], v[36:37], off
	global_load_dwordx4 v[114:117], v[34:35], off
.Lgqa1_noload:
	s_add_i32 s15, s35, s34
	s_add_i32 s16, s15, 48
	s_cmpk_lt_u32 s16, 0xfc1
	s_cbranch_scc0 .Lgqa1_slow
	ds_read_b128 v[66:69], v127
	ds_read_b128 v[70:73], v127 offset:4608
	ds_read_b128 v[74:77], v127 offset:32
	ds_read_b128 v[78:81], v127 offset:4640
	ds_read_b128 v[82:85], v127 offset:64
	ds_read_b128 v[86:89], v127 offset:4672
	ds_read_b128 v[90:93], v127 offset:96
	ds_read_b128 v[94:97], v127 offset:4704
	ds_read2_b32 v[34:35], v131 offset0:0 offset1:1
	ds_read2_b32 v[36:37], v131 offset0:2 offset1:3
	ds_read2_b32 v[38:39], v131 offset0:8 offset1:9
	ds_read2_b32 v[40:41], v131 offset0:10 offset1:11
	ds_read2_b32 v[42:43], v131 offset0:16 offset1:17
	ds_read2_b32 v[44:45], v131 offset0:18 offset1:19
	ds_read2_b32 v[46:47], v131 offset0:24 offset1:25
	ds_read2_b32 v[48:49], v131 offset0:26 offset1:27
	ds_read2_b32 v[50:51], v131 offset0:32 offset1:33
	ds_read2_b32 v[52:53], v131 offset0:34 offset1:35
	ds_read2_b32 v[54:55], v131 offset0:40 offset1:41
	ds_read2_b32 v[56:57], v131 offset0:42 offset1:43
	ds_read2_b32 v[58:59], v131 offset0:48 offset1:49
	ds_read2_b32 v[60:61], v131 offset0:50 offset1:51
	ds_read2_b32 v[62:63], v131 offset0:56 offset1:57
	ds_read2_b32 v[64:65], v131 offset0:58 offset1:59
	s_waitcnt lgkmcnt(8)
	v_mfma_f32_32x32x16_bf16 v[34:49], v[66:69], v[98:101], v[34:49]
	s_waitcnt lgkmcnt(0)
	v_mfma_f32_32x32x16_bf16 v[50:65], v[70:73], v[98:101], v[50:65]
	v_mfma_f32_32x32x16_bf16 v[34:49], v[74:77], v[102:105], v[34:49]
	v_mfma_f32_32x32x16_bf16 v[50:65], v[78:81], v[102:105], v[50:65]
	v_mfma_f32_32x32x16_bf16 v[34:49], v[82:85], v[106:109], v[34:49]
	v_mfma_f32_32x32x16_bf16 v[50:65], v[86:89], v[106:109], v[50:65]
	v_mfma_f32_32x32x16_bf16 v[34:49], v[90:93], v[110:113], v[34:49]
	v_mfma_f32_32x32x16_bf16 v[50:65], v[94:97], v[110:113], v[50:65]
	s_branch .Lgqa1_tail
.Lgqa1_slow:
	ds_read_b128 v[34:37], v127 offset:4608
	ds_read_b128 v[38:41], v127
	ds_read_b128 v[42:45], v127 offset:32
	s_add_i32 s15, s35, s34
	s_add_i32 s16, s15, 48
	s_waitcnt lgkmcnt(2)
	v_mfma_f32_32x32x16_bf16 v[66:81], v[34:37], v[98:101], 0
	ds_read_b128 v[34:37], v127 offset:4640
	s_mov_b64 s[0:1], -1
	s_cmpk_lt_u32 s16, 0xfc1
	s_waitcnt lgkmcnt(2)
	v_mfma_f32_32x32x16_bf16 v[82:97], v[38:41], v[98:101], 0
	s_waitcnt lgkmcnt(1)
	v_mfma_f32_32x32x16_bf16 v[82:97], v[42:45], v[102:105], v[82:97]
	s_waitcnt lgkmcnt(0)
	v_mfma_f32_32x32x16_bf16 v[66:81], v[34:37], v[102:105], v[66:81]
	ds_read_b128 v[34:37], v127 offset:64
	ds_read_b128 v[38:41], v127 offset:4672
	s_waitcnt lgkmcnt(1)
	v_mfma_f32_32x32x16_bf16 v[82:97], v[34:37], v[106:109], v[82:97]
	s_waitcnt lgkmcnt(0)
	v_mfma_f32_32x32x16_bf16 v[66:81], v[38:41], v[106:109], v[66:81]
	ds_read_b128 v[34:37], v127 offset:96
	ds_read_b128 v[38:41], v127 offset:4704
	s_waitcnt lgkmcnt(1)
	v_mfma_f32_32x32x16_bf16 v[82:97], v[34:37], v[110:113], v[82:97]
	s_waitcnt lgkmcnt(0)
	v_mfma_f32_32x32x16_bf16 v[66:81], v[38:41], v[110:113], v[66:81]
	v_add_u32_e32 v49, s34, v132
	v_add_u32_e32 v134, s34, v133
	v_add_u32_e32 v35, 64, v49
	v_add_u32_e32 v34, 0xc0, v134
	v_cmp_gt_i32_e32 vcc, 16, v35
	v_cmp_gt_u32_e64 s[44:45], s6, v34
	s_or_b64 s[0:1], vcc, s[44:45]
	v_cmp_gt_i32_e32 vcc, s37, v35
	s_and_b64 s[28:29], vcc, s[0:1]
	v_mov_b32_e32 v50, 0xf149f2ca
	v_mov_b32_e32 v34, 0xf149f2ca
	s_and_saveexec_b64 s[0:1], s[28:29]
	s_cbranch_execz .LBB0_1084
	v_add_u32_e32 v34, 64, v134
	v_med3_i32 v34, v34, s87, v240
	v_lshl_add_u32 v34, v34, 2, s31
	ds_read_b32 v34, v34 offset:512
	s_waitcnt lgkmcnt(0)
	v_add_f32_e32 v34, v82, v34

; #define LAS __attribute__((address_space(3)))
; template <int MODE> __device__ __forceinline__ void attn_unit(const AttnP& P, int u, LAS char* lds, bool fill) {
;     ...
;         float mx = p0[0];
; #pragma unroll
;         for (int r = 1; r < 16; ++r) mx = fmaxf(mx, p0[r]);
; #pragma unroll
;         for (int r = 0; r < 16; ++r) mx = fmaxf(mx, p1[r]);
;         { const auto rr = __builtin_amdgcn_permlane32_swap(__float_as_uint(mx), __float_as_uint(mx), false, false); mx = fmaxf(__uint_as_float(rr[0]), __uint_as_float(rr[1])); }
;         if (__any(mx > mrun + 8.0f)) {
;             const float mnew = fmaxf(mrun, mx); const float f = __builtin_amdgcn_exp2f(mrun - mnew); mrun = mnew; lrun *= f;
; #pragma unroll
;             for (int d = 0; d < ND; ++d)
; #pragma unroll
;                 for (int r = 0; r < 16; ++r) o[d][r] *= f;
;         }
;         float sacc = 0.f;
; #pragma unroll
;         for (int r = 0; r < 16; ++r) { p0[r] = __builtin_amdgcn_exp2f(p0[r] - mrun); p1[r] = __builtin_amdgcn_exp2f(p1[r] - mrun); sacc += p0[r] + p1[r]; }
;         lrun += sacc;
;         bf16x8 pf[4];
;         { u32x4 a;
;           a.x = cvtpk(p0[0], p0[1]); a.y = cvtpk(p0[2], p0[3]); a.z = cvtpk(p0[4], p0[5]); a.w = cvtpk(p0[6], p0[7]); pf[0] = __builtin_bit_cast(bf16x8, a);
;           a.x = cvtpk(p0[8], p0[9]); a.y = cvtpk(p0[10], p0[11]); a.z = cvtpk(p0[12], p0[13]); a.w = cvtpk(p0[14], p0[15]); pf[1] = __builtin_bit_cast(bf16x8, a);
;           a.x = cvtpk(p1[0], p1[1]); a.y = cvtpk(p1[2], p1[3]); a.z = cvtpk(p1[4], p1[5]); a.w = cvtpk(p1[6], p1[7]); pf[2] = __builtin_bit_cast(bf16x8, a);
;           a.x = cvtpk(p1[8], p1[9]); a.y = cvtpk(p1[10], p1[11]); a.z = cvtpk(p1[12], p1[13]); a.w = cvtpk(p1[14], p1[15]); pf[3] = __builtin_bit_cast(bf16x8, a); }
; #pragma unroll
;         for (int d = 0; d < ND; ++d) {
;             const int vslot = MODE == 0 ? 2 + (d >> 1) : MODE == 1 ? kslot + 1 : 1;
;             const LAS char* vb = lds + vslot * ASLOT + vrow * APITCH + (d & 1) * 64 + vcolb;
; #pragma unroll
;             for (int ks = 0; ks < 4; ++ks) {
;                 const s16x4 vl = vtr(vb + (16 * ks) * APITCH), vh = vtr(vb + (16 * ks + 8) * APITCH);
;                 const bf16x8 vf = (bf16x8){vl[0], vl[1], vl[2], vl[3], vh[0], vh[1], vh[2], vh[3]};
;                 o[d] = __builtin_amdgcn_mfma_f32_32x32x16_bf16(vf, pf[ks], o[d], 0, 0, 0);
;             }
;         }
.Lgqa1_tail:
	ds_read_b64_tr_b16 v[66:67], v129 offset:9216
	ds_read_b64_tr_b16 v[68:69], v129 offset:10368
	ds_read_b64_tr_b16 v[70:71], v129 offset:9280
	ds_read_b64_tr_b16 v[72:73], v129 offset:10432
	ds_read_b64_tr_b16 v[74:75], v129 offset:11520
	ds_read_b64_tr_b16 v[76:77], v129 offset:12672
	ds_read_b64_tr_b16 v[78:79], v129 offset:11584
	ds_read_b64_tr_b16 v[80:81], v129 offset:12736
	ds_read_b64_tr_b16 v[82:83], v129 offset:13824
	ds_read_b64_tr_b16 v[84:85], v129 offset:14976
	ds_read_b64_tr_b16 v[86:87], v129 offset:13888
	ds_read_b64_tr_b16 v[88:89], v129 offset:15040
	ds_read_b64_tr_b16 v[90:91], v129 offset:16128
	ds_read_b64_tr_b16 v[92:93], v129 offset:17280
	ds_read_b64_tr_b16 v[94:95], v129 offset:16192
	ds_read_b64_tr_b16 v[96:97], v129 offset:17344
	v_max3_f32 v134, v34, v35, v36
	v_max3_f32 v135, v50, v51, v52
	v_max3_f32 v134, v134, v37, v38
	v_max3_f32 v135, v135, v53, v54
	v_max3_f32 v134, v134, v39, v40
	v_max3_f32 v135, v135, v55, v56
	v_max3_f32 v134, v134, v41, v42
	v_max3_f32 v135, v135, v57, v58
	v_max3_f32 v134, v134, v43, v44
	v_max3_f32 v135, v135, v59, v60
	v_max3_f32 v134, v134, v45, v46
	v_max3_f32 v135, v135, v61, v62
	v_max3_f32 v134, v134, v47, v48
	v_max3_f32 v135, v135, v63, v64
	v_max_f32_e32 v134, v134, v49
	v_max_f32_e32 v135, v135, v65
	v_max_f32_e32 v134, v134, v135
	v_mov_b32_e32 v135, v134
	s_nop 1
	v_permlane32_swap_b32_e32 v134, v135
	v_max_f32_e32 v134, v134, v135
	v_add_f32_e32 v135, 0x41000000, v128
	v_cmp_gt_f32_e32 vcc, v134, v135
	s_cbranch_vccz .Lgqa1_noresc
	v_max_f32_e32 v134, v128, v134
	v_sub_f32_e32 v135, v128, v134
	v_exp_f32_e32 v135, v135
	v_mov_b32_e32 v128, v134
	v_mul_f32_e32 v18, v18, v135
	v_mul_f32_e32 v19, v19, v135
	v_mul_f32_e32 v20, v20, v135
	v_mul_f32_e32 v21, v21, v135
	v_mul_f32_e32 v22, v22, v135
	v_mul_f32_e32 v23, v23, v135
	v_mul_f32_e32 v24, v24, v135
	v_mul_f32_e32 v25, v25, v135
	v_mul_f32_e32 v26, v26, v135
	v_mul_f32_e32 v27, v27, v135
	v_mul_f32_e32 v28, v28, v135
	v_mul_f32_e32 v29, v29, v135
	v_mul_f32_e32 v30, v30, v135
	v_mul_f32_e32 v31, v31, v135
	v_mul_f32_e32 v32, v32, v135
	v_mul_f32_e32 v33, v33, v135
	v_mul_f32_e32 v2, v2, v135
	v_mul_f32_e32 v3, v3, v135
	v_mul_f32_e32 v4, v4, v135
	v_mul_f32_e32 v5, v5, v135
	v_mul_f32_e32 v6, v6, v135
	v_mul_f32_e32 v7, v7, v135
	v_mul_f32_e32 v8, v8, v135
	v_mul_f32_e32 v9, v9, v135
	v_mul_f32_e32 v10, v10, v135
	v_mul_f32_e32 v11, v11, v135
	v_mul_f32_e32 v12, v12, v135
	v_mul_f32_e32 v13, v13, v135
	v_mul_f32_e32 v14, v14, v135
	v_mul_f32_e32 v15, v15, v135
	v_mul_f32_e32 v16, v16, v135
	v_mul_f32_e32 v17, v17, v135
	v_mul_f32_e32 v130, v130, v135
	s_nop 1
.Lgqa1_noresc:
	v_sub_f32_e32 v34, v34, v128
	v_sub_f32_e32 v35, v35, v128
	v_sub_f32_e32 v36, v36, v128
	v_sub_f32_e32 v37, v37, v128
	v_sub_f32_e32 v38, v38, v128
	v_sub_f32_e32 v39, v39, v128
	v_sub_f32_e32 v40, v40, v128
	v_sub_f32_e32 v41, v41, v128
	v_exp_f32_e32 v34, v34
	v_exp_f32_e32 v35, v35
	v_exp_f32_e32 v36, v36
	v_exp_f32_e32 v37, v37
	v_exp_f32_e32 v38, v38
	v_exp_f32_e32 v39, v39
	v_exp_f32_e32 v40, v40
	v_exp_f32_e32 v41, v41
	v_add_f32_e32 v130, v130, v34
	v_add_f32_e32 v130, v130, v35
	v_add_f32_e32 v130, v130, v36
	v_add_f32_e32 v130, v130, v37
	v_add_f32_e32 v130, v130, v38
	v_add_f32_e32 v130, v130, v39
	v_add_f32_e32 v130, v130, v40
	v_add_f32_e32 v130, v130, v41
	v_cvt_pk_bf16_f32 v34, v34, v35
	v_cvt_pk_bf16_f32 v35, v36, v37
	v_cvt_pk_bf16_f32 v36, v38, v39
	v_cvt_pk_bf16_f32 v37, v40, v41
	s_nop 0
	s_waitcnt lgkmcnt(14)
	v_mfma_f32_32x32x16_bf16 v[18:33], v[66:69], v[34:37], v[18:33]
	s_waitcnt lgkmcnt(12)
	v_mfma_f32_32x32x16_bf16 v[2:17], v[70:73], v[34:37], v[2:17]
	v_sub_f32_e32 v42, v42, v128
	v_sub_f32_e32 v43, v43, v128
	v_sub_f32_e32 v44, v44, v128
	v_sub_f32_e32 v45, v45, v128
	v_sub_f32_e32 v46, v46, v128
	v_sub_f32_e32 v47, v47, v128
	v_sub_f32_e32 v48, v48, v128
	v_sub_f32_e32 v49, v49, v128
	v_exp_f32_e32 v42, v42
	v_exp_f32_e32 v43, v43
	v_exp_f32_e32 v44, v44
	v_exp_f32_e32 v45, v45
	v_exp_f32_e32 v46, v46
	v_exp_f32_e32 v47, v47
	v_exp_f32_e32 v48, v48
	v_exp_f32_e32 v49, v49
	v_add_f32_e32 v130, v130, v42
	v_add_f32_e32 v130, v130, v43
	v_add_f32_e32 v130, v130, v44
	v_add_f32_e32 v130, v130, v45
	v_add_f32_e32 v130, v130, v46
	v_add_f32_e32 v130, v130, v47
	v_add_f32_e32 v130, v130, v48
	v_add_f32_e32 v130, v130, v49
	v_cvt_pk_bf16_f32 v38, v42, v43
	v_cvt_pk_bf16_f32 v39, v44, v45
	v_cvt_pk_bf16_f32 v40, v46, v47
	v_cvt_pk_bf16_f32 v41, v48, v49
	s_nop 0
	s_waitcnt lgkmcnt(10)
	v_mfma_f32_32x32x16_bf16 v[18:33], v[74:77], v[38:41], v[18:33]
	s_waitcnt lgkmcnt(8)
	v_mfma_f32_32x32x16_bf16 v[2:17], v[78:81], v[38:41], v[2:17]
	v_sub_f32_e32 v50, v50, v128
	v_sub_f32_e32 v51, v51, v128
	v_sub_f32_e32 v52, v52, v128
	v_sub_f32_e32 v53, v53, v128
	v_sub_f32_e32 v54, v54, v128
	v_sub_f32_e32 v55, v55, v128
	v_sub_f32_e32 v56, v56, v128
	v_sub_f32_e32 v57, v57, v128
	v_exp_f32_e32 v50, v50
	v_exp_f32_e32 v51, v51
	v_exp_f32_e32 v52, v52
	v_exp_f32_e32 v53, v53
	v_exp_f32_e32 v54, v54
	v_exp_f32_e32 v55, v55
	v_exp_f32_e32 v56, v56
	v_exp_f32_e32 v57, v57
	v_add_f32_e32 v130, v130, v50
	v_add_f32_e32 v130, v130, v51
	v_add_f32_e32 v130, v130, v52
	v_add_f32_e32 v130, v130, v53
	v_add_f32_e32 v130, v130, v54
	v_add_f32_e32 v130, v130, v55
	v_add_f32_e32 v130, v130, v56
	v_add_f32_e32 v130, v130, v57
	v_cvt_pk_bf16_f32 v42, v50, v51
	v_cvt_pk_bf16_f32 v43, v52, v53
	v_cvt_pk_bf16_f32 v44, v54, v55
	v_cvt_pk_bf16_f32 v45, v56, v57
	s_nop 0
	s_waitcnt lgkmcnt(6)
	v_mfma_f32_32x32x16_bf16 v[18:33], v[82:85], v[42:45], v[18:33]
	s_waitcnt lgkmcnt(4)
	v_mfma_f32_32x32x16_bf16 v[2:17], v[86:89], v[42:45], v[2:17]
	v_sub_f32_e32 v58, v58, v128
	v_sub_f32_e32 v59, v59, v128
	v_sub_f32_e32 v60, v60, v128
	v_sub_f32_e32 v61, v61, v128
	v_sub_f32_e32 v62, v62, v128
	v_sub_f32_e32 v63, v63, v128
	v_sub_f32_e32 v64, v64, v128
	v_sub_f32_e32 v65, v65, v128
	v_exp_f32_e32 v58, v58
	v_exp_f32_e32 v59, v59
	v_exp_f32_e32 v60, v60
	v_exp_f32_e32 v61, v61
	v_exp_f32_e32 v62, v62
	v_exp_f32_e32 v63, v63
	v_exp_f32_e32 v64, v64
	v_exp_f32_e32 v65, v65
	v_add_f32_e32 v130, v130, v58
	v_add_f32_e32 v130, v130, v59
	v_add_f32_e32 v130, v130, v60
	v_add_f32_e32 v130, v130, v61
	v_add_f32_e32 v130, v130, v62
	v_add_f32_e32 v130, v130, v63
	v_add_f32_e32 v130, v130, v64
	v_add_f32_e32 v130, v130, v65
	v_cvt_pk_bf16_f32 v46, v58, v59
	v_cvt_pk_bf16_f32 v47, v60, v61
	v_cvt_pk_bf16_f32 v48, v62, v63
	v_cvt_pk_bf16_f32 v49, v64, v65
	s_nop 0
	s_waitcnt lgkmcnt(2)
	v_mfma_f32_32x32x16_bf16 v[18:33], v[90:93], v[46:49], v[18:33]
	s_waitcnt lgkmcnt(0)
	v_mfma_f32_32x32x16_bf16 v[2:17], v[94:97], v[46:49], v[2:17]
	s_add_i32 s34, s34, 64
	v_add_u32_e32 v131, 0x100, v131
	s_cmp_eq_u32 s30, s38
	s_cbranch_scc1 .LBB0_1152
	s_branch .LBB0_1079

; #define LAS __attribute__((address_space(3)))
; template <int MODE> __device__ __forceinline__ void attn_unit(const AttnP& P, int u, LAS char* lds, bool fill) {
;     ...
;     for (int t = 0; t < nt; ++t) {
;         __syncthreads();
; #pragma unroll
;         for (int s = 0; s < NS; ++s) *(LAS u32x4*)(lds + s * ASLOT + lrow * APITCH + lch * 16) = pre[s];
;         __syncthreads();
;         if (t + 1 < nt) ISSUE(t + 1);
;         const int tok0 = TILE_TOK0(t);
;         f32x16 p0, p1;
; #pragma unroll
;         for (int r = 0; r < 16; ++r) { p0[r] = 0.f; p1[r] = 0.f; }
; #pragma unroll
;         for (int ds = 0; ds < 4; ++ds) {
;             const bf16x8 k0 = *(const LAS bf16x8*)(kb + ds * 32);
;             const bf16x8 k1 = *(const LAS bf16x8*)(kb + 32 * APITCH + ds * 32);
;             p0 = __builtin_amdgcn_mfma_f32_32x32x16_bf16(k0, qr[ds], p0, 0, 0, 0);
;             p1 = __builtin_amdgcn_mfma_f32_32x32x16_bf16(k1, qr[ds], p1, 0, 0, 0);
;         }
;         if (MODE == 0) {
;             const bool farl = (tok0 + 63 + 128 <= qtok0), farr = (tok0 - (qtok0 + 31) >= 128) && (tok0 + 64 <= LT);
;             if (farl || farr) { const float cb = farl ? mytab[0] : mytab[256];
; #pragma unroll
;                 for (int r = 0; r < 16; ++r) { p0[r] += cb; p1[r] += cb; } }
;             else {
; #pragma unroll
;                 for (int r = 0; r < 16; ++r) { const int tk0 = tok0 + crow(r, hi), tk1 = tk0 + 32;
;                     int i0 = tk0 - tq + 128; i0 = i0 < 0 ? 0 : (i0 > 256 ? 256 : i0); int i1 = tk1 - tq + 128; i1 = i1 < 0 ? 0 : (i1 > 256 ? 256 : i1);
;                     p0[r] = tk0 < LT ? p0[r] + mytab[i0] : NEGV; p1[r] = tk1 < LT ? p1[r] + mytab[i1] : NEGV; } }
;         } else if (MODE == 2) {
;           if (tok0 >= NMETA && tok0 + 64 <= LT) {
;             const LAS float* t2 = mytab2 + (tok0 - tq + 191 + 4 * hi);
; #pragma unroll
;             for (int r = 0; r < 16; ++r) { p0[r] += t2[(r & 3) + 8 * (r >> 2)]; p1[r] += t2[(r & 3) + 8 * (r >> 2) + 32]; }
;           } else
; #pragma unroll
;             for (int r = 0; r < 16; ++r) { const int tk0 = tok0 + crow(r, hi), tk1 = tk0 + 32; const int r0 = tk0 - tq, r1 = tk1 - tq;
;                 int i0 = r0 + 128; i0 = i0 < 0 ? 0 : (i0 > 256 ? 256 : i0); int i1 = r1 + 128; i1 = i1 < 0 ? 0 : (i1 > 256 ? 256 : i1);
.LBB0_1266:
	s_add_i32 s39, s39, 1
	s_waitcnt lgkmcnt(0)
	s_barrier
	s_waitcnt vmcnt(1)
	ds_write_b128 v0, v[118:121]
	s_waitcnt vmcnt(0)
	ds_write_b128 v0, v[114:117] offset:9216
	s_waitcnt lgkmcnt(0)
	s_barrier
	s_cmp_ge_i32 s39, s31
	s_cbranch_scc1 .Lgqa2_noload
	s_add_i32 s15, s35, 0x80
	s_add_i32 s16, s14, s35
	s_and_b64 s[0:1], s[46:47], exec
	s_cselect_b32 s0, s16, s15
	v_add_u32_e32 v34, s0, v126
	v_min_i32_e32 v34, 0x100f, v34
	v_mad_i64_i32 v[34:35], s[0:1], v34, s51, v[122:123]
	v_lshl_add_u64 v[36:37], s[48:49], 1, v[34:35]
	v_lshl_add_u64 v[34:35], s[58:59], 1, v[34:35]
	global_load_dwordx4 v[118:121], v[36:37], off
	global_load_dwordx4 v[114:117], v[34:35], off
.Lgqa2_noload:
	s_add_i32 s15, s38, s35
	s_add_i32 s16, s15, 48
	s_cmpk_lt_u32 s16, 0xfc1
	s_cbranch_scc0 .Lgqa2_slow
	ds_read_b128 v[66:69], v127
	ds_read_b128 v[70:73], v127 offset:4608
	ds_read_b128 v[74:77], v127 offset:32
	ds_read_b128 v[78:81], v127 offset:4640
	ds_read_b128 v[82:85], v127 offset:64
	ds_read_b128 v[86:89], v127 offset:4672
	ds_read_b128 v[90:93], v127 offset:96
	ds_read_b128 v[94:97], v127 offset:4704
	ds_read2_b32 v[34:35], v131 offset0:0 offset1:1
	ds_read2_b32 v[36:37], v131 offset0:2 offset1:3
	ds_read2_b32 v[38:39], v131 offset0:8 offset1:9
	ds_read2_b32 v[40:41], v131 offset0:10 offset1:11
	ds_read2_b32 v[42:43], v131 offset0:16 offset1:17
	ds_read2_b32 v[44:45], v131 offset0:18 offset1:19
	ds_read2_b32 v[46:47], v131 offset0:24 offset1:25
	ds_read2_b32 v[48:49], v131 offset0:26 offset1:27
	ds_read2_b32 v[50:51], v131 offset0:32 offset1:33
	ds_read2_b32 v[52:53], v131 offset0:34 offset1:35
	ds_read2_b32 v[54:55], v131 offset0:40 offset1:41
	ds_read2_b32 v[56:57], v131 offset0:42 offset1:43
	ds_read2_b32 v[58:59], v131 offset0:48 offset1:49
	ds_read2_b32 v[60:61], v131 offset0:50 offset1:51
	ds_read2_b32 v[62:63], v131 offset0:56 offset1:57
	ds_read2_b32 v[64:65], v131 offset0:58 offset1:59
	s_waitcnt lgkmcnt(8)
	v_mfma_f32_32x32x16_bf16 v[34:49], v[66:69], v[98:101], v[34:49]
	s_waitcnt lgkmcnt(0)
	v_mfma_f32_32x32x16_bf16 v[50:65], v[70:73], v[98:101], v[50:65]
	v_mfma_f32_32x32x16_bf16 v[34:49], v[74:77], v[102:105], v[34:49]
	v_mfma_f32_32x32x16_bf16 v[50:65], v[78:81], v[102:105], v[50:65]
	v_mfma_f32_32x32x16_bf16 v[34:49], v[82:85], v[106:109], v[34:49]
	v_mfma_f32_32x32x16_bf16 v[50:65], v[86:89], v[106:109], v[50:65]
	v_mfma_f32_32x32x16_bf16 v[34:49], v[90:93], v[110:113], v[34:49]
	v_mfma_f32_32x32x16_bf16 v[50:65], v[94:97], v[110:113], v[50:65]
	s_branch .Lgqa2_tail
.Lgqa2_slow:
	ds_read_b128 v[34:37], v127 offset:4608
	ds_read_b128 v[38:41], v127
	ds_read_b128 v[42:45], v127 offset:32
	s_add_i32 s15, s38, s35
	s_add_i32 s16, s15, 48
	s_waitcnt lgkmcnt(2)
	v_mfma_f32_32x32x16_bf16 v[66:81], v[34:37], v[98:101], 0
	ds_read_b128 v[34:37], v127 offset:4640
	s_mov_b64 s[0:1], -1
	s_cmpk_lt_u32 s16, 0xfc1
	s_waitcnt lgkmcnt(2)
	v_mfma_f32_32x32x16_bf16 v[82:97], v[38:41], v[98:101], 0
	s_waitcnt lgkmcnt(1)
	v_mfma_f32_32x32x16_bf16 v[82:97], v[42:45], v[102:105], v[82:97]
	s_waitcnt lgkmcnt(0)
	v_mfma_f32_32x32x16_bf16 v[66:81], v[34:37], v[102:105], v[66:81]
	ds_read_b128 v[34:37], v127 offset:64
	ds_read_b128 v[38:41], v127 offset:4672
	s_waitcnt lgkmcnt(1)
	v_mfma_f32_32x32x16_bf16 v[82:97], v[34:37], v[106:109], v[82:97]
	s_waitcnt lgkmcnt(0)
	v_mfma_f32_32x32x16_bf16 v[66:81], v[38:41], v[106:109], v[66:81]
	ds_read_b128 v[34:37], v127 offset:96
	ds_read_b128 v[38:41], v127 offset:4704
	s_waitcnt lgkmcnt(1)
	v_mfma_f32_32x32x16_bf16 v[82:97], v[34:37], v[110:113], v[82:97]
	s_waitcnt lgkmcnt(0)
	v_mfma_f32_32x32x16_bf16 v[66:81], v[38:41], v[110:113], v[66:81]
	v_add_u32_e32 v49, s35, v132
	v_add_u32_e32 v134, s35, v133
	v_add_u32_e32 v35, 64, v49
	v_add_u32_e32 v34, 0xc0, v134
	v_cmp_gt_i32_e32 vcc, 16, v35
	v_cmp_gt_u32_e64 s[44:45], s6, v34
	s_or_b64 s[0:1], vcc, s[44:45]
	v_cmp_gt_i32_e32 vcc, s37, v35
	s_and_b64 s[28:29], vcc, s[0:1]
	v_mov_b32_e32 v50, 0xf149f2ca
	v_mov_b32_e32 v34, 0xf149f2ca
	s_and_saveexec_b64 s[0:1], s[28:29]
	s_cbranch_execz .LBB0_1271
	v_add_u32_e32 v34, 64, v134
	v_med3_i32 v34, v34, s87, v240
	v_lshl_add_u32 v34, v34, 2, s34
	ds_read_b32 v34, v34 offset:512
	s_waitcnt lgkmcnt(0)
	v_add_f32_e32 v34, v82, v34

; #define LAS __attribute__((address_space(3)))
; __device__ __forceinline__ unsigned cvtpk(float lo, float hi) { f32x2_t v = {lo, hi}; bf16x2_t b = __builtin_convertvector(v, bf16x2_t); return __builtin_bit_cast(unsigned, b); }
; __device__ __forceinline__ s16x4 vtr(const LAS char* p) { return __builtin_bit_cast(s16x4, __builtin_amdgcn_ds_read_tr16_b64_v4i16((LAS s16x4*)p)); }
; template <int MODE> __device__ __forceinline__ void attn_unit(const AttnP& P, int u, LAS char* lds, bool fill) {
;     ...
;         float sacc = 0.f;
; #pragma unroll
;         for (int r = 0; r < 16; ++r) { p0[r] = __builtin_amdgcn_exp2f(p0[r] - mrun); p1[r] = __builtin_amdgcn_exp2f(p1[r] - mrun); sacc += p0[r] + p1[r]; }
;         lrun += sacc;
;         bf16x8 pf[4];
;         { u32x4 a;
;           a.x = cvtpk(p0[0], p0[1]); a.y = cvtpk(p0[2], p0[3]); a.z = cvtpk(p0[4], p0[5]); a.w = cvtpk(p0[6], p0[7]); pf[0] = __builtin_bit_cast(bf16x8, a);
;           a.x = cvtpk(p0[8], p0[9]); a.y = cvtpk(p0[10], p0[11]); a.z = cvtpk(p0[12], p0[13]); a.w = cvtpk(p0[14], p0[15]); pf[1] = __builtin_bit_cast(bf16x8, a);
;           a.x = cvtpk(p1[0], p1[1]); a.y = cvtpk(p1[2], p1[3]); a.z = cvtpk(p1[4], p1[5]); a.w = cvtpk(p1[6], p1[7]); pf[2] = __builtin_bit_cast(bf16x8, a);
;           a.x = cvtpk(p1[8], p1[9]); a.y = cvtpk(p1[10], p1[11]); a.z = cvtpk(p1[12], p1[13]); a.w = cvtpk(p1[14], p1[15]); pf[3] = __builtin_bit_cast(bf16x8, a); }
; #pragma unroll
;         for (int d = 0; d < ND; ++d) {
;             const int vslot = MODE == 0 ? 2 + (d >> 1) : MODE == 1 ? kslot + 1 : 1;
;             const LAS char* vb = lds + vslot * ASLOT + vrow * APITCH + (d & 1) * 64 + vcolb;
; #pragma unroll
;             for (int ks = 0; ks < 4; ++ks) {
;                 const s16x4 vl = vtr(vb + (16 * ks) * APITCH), vh = vtr(vb + (16 * ks + 8) * APITCH);
;                 const bf16x8 vf = (bf16x8){vl[0], vl[1], vl[2], vl[3], vh[0], vh[1], vh[2], vh[3]};
;                 o[d] = __builtin_amdgcn_mfma_f32_32x32x16_bf16(vf, pf[ks], o[d], 0, 0, 0);
;             }
;         }
.Lgqa2_noresc:
	v_sub_f32_e32 v34, v34, v128
	v_sub_f32_e32 v35, v35, v128
	v_sub_f32_e32 v36, v36, v128
	v_sub_f32_e32 v37, v37, v128
	v_sub_f32_e32 v38, v38, v128
	v_sub_f32_e32 v39, v39, v128
	v_sub_f32_e32 v40, v40, v128
	v_sub_f32_e32 v41, v41, v128
	v_exp_f32_e32 v34, v34
	v_exp_f32_e32 v35, v35
	v_exp_f32_e32 v36, v36
	v_exp_f32_e32 v37, v37
	v_exp_f32_e32 v38, v38
	v_exp_f32_e32 v39, v39
	v_exp_f32_e32 v40, v40
	v_exp_f32_e32 v41, v41
	v_add_f32_e32 v130, v130, v34
	v_add_f32_e32 v130, v130, v35
	v_add_f32_e32 v130, v130, v36
	v_add_f32_e32 v130, v130, v37
	v_add_f32_e32 v130, v130, v38
	v_add_f32_e32 v130, v130, v39
	v_add_f32_e32 v130, v130, v40
	v_add_f32_e32 v130, v130, v41
	v_cvt_pk_bf16_f32 v34, v34, v35
	v_cvt_pk_bf16_f32 v35, v36, v37
	v_cvt_pk_bf16_f32 v36, v38, v39
	v_cvt_pk_bf16_f32 v37, v40, v41
	s_nop 0
	s_waitcnt lgkmcnt(14)
	v_mfma_f32_32x32x16_bf16 v[18:33], v[66:69], v[34:37], v[18:33]
	s_waitcnt lgkmcnt(12)
	v_mfma_f32_32x32x16_bf16 v[2:17], v[70:73], v[34:37], v[2:17]
	v_sub_f32_e32 v42, v42, v128
	v_sub_f32_e32 v43, v43, v128
	v_sub_f32_e32 v44, v44, v128
	v_sub_f32_e32 v45, v45, v128
	v_sub_f32_e32 v46, v46, v128
	v_sub_f32_e32 v47, v47, v128
	v_sub_f32_e32 v48, v48, v128
	v_sub_f32_e32 v49, v49, v128
	v_exp_f32_e32 v42, v42
	v_exp_f32_e32 v43, v43
	v_exp_f32_e32 v44, v44
	v_exp_f32_e32 v45, v45
	v_exp_f32_e32 v46, v46
	v_exp_f32_e32 v47, v47
	v_exp_f32_e32 v48, v48
	v_exp_f32_e32 v49, v49
	v_add_f32_e32 v130, v130, v42
	v_add_f32_e32 v130, v130, v43
	v_add_f32_e32 v130, v130, v44
	v_add_f32_e32 v130, v130, v45
	v_add_f32_e32 v130, v130, v46
	v_add_f32_e32 v130, v130, v47
	v_add_f32_e32 v130, v130, v48
	v_add_f32_e32 v130, v130, v49
	v_cvt_pk_bf16_f32 v38, v42, v43
	v_cvt_pk_bf16_f32 v39, v44, v45
	v_cvt_pk_bf16_f32 v40, v46, v47
	v_cvt_pk_bf16_f32 v41, v48, v49
	s_nop 0
	s_waitcnt lgkmcnt(10)
	v_mfma_f32_32x32x16_bf16 v[18:33], v[74:77], v[38:41], v[18:33]
	s_waitcnt lgkmcnt(8)
	v_mfma_f32_32x32x16_bf16 v[2:17], v[78:81], v[38:41], v[2:17]
	v_sub_f32_e32 v50, v50, v128
	v_sub_f32_e32 v51, v51, v128
	v_sub_f32_e32 v52, v52, v128
	v_sub_f32_e32 v53, v53, v128
	v_sub_f32_e32 v54, v54, v128
	v_sub_f32_e32 v55, v55, v128
	v_sub_f32_e32 v56, v56, v128
	v_sub_f32_e32 v57, v57, v128
	v_exp_f32_e32 v50, v50
	v_exp_f32_e32 v51, v51
	v_exp_f32_e32 v52, v52
	v_exp_f32_e32 v53, v53
	v_exp_f32_e32 v54, v54
	v_exp_f32_e32 v55, v55
	v_exp_f32_e32 v56, v56
	v_exp_f32_e32 v57, v57
	v_add_f32_e32 v130, v130, v50
	v_add_f32_e32 v130, v130, v51
	v_add_f32_e32 v130, v130, v52
	v_add_f32_e32 v130, v130, v53
	v_add_f32_e32 v130, v130, v54
	v_add_f32_e32 v130, v130, v55
	v_add_f32_e32 v130, v130, v56
	v_add_f32_e32 v130, v130, v57
	v_cvt_pk_bf16_f32 v42, v50, v51
	v_cvt_pk_bf16_f32 v43, v52, v53
	v_cvt_pk_bf16_f32 v44, v54, v55
	v_cvt_pk_bf16_f32 v45, v56, v57
	s_nop 0
	s_waitcnt lgkmcnt(6)
	v_mfma_f32_32x32x16_bf16 v[18:33], v[82:85], v[42:45], v[18:33]
	s_waitcnt lgkmcnt(4)
	v_mfma_f32_32x32x16_bf16 v[2:17], v[86:89], v[42:45], v[2:17]
	v_sub_f32_e32 v58, v58, v128
	v_sub_f32_e32 v59, v59, v128
	v_sub_f32_e32 v60, v60, v128
	v_sub_f32_e32 v61, v61, v128
	v_sub_f32_e32 v62, v62, v128
	v_sub_f32_e32 v63, v63, v128
	v_sub_f32_e32 v64, v64, v128
	v_sub_f32_e32 v65, v65, v128
	v_exp_f32_e32 v58, v58
	v_exp_f32_e32 v59, v59
	v_exp_f32_e32 v60, v60
	v_exp_f32_e32 v61, v61
	v_exp_f32_e32 v62, v62
	v_exp_f32_e32 v63, v63
	v_exp_f32_e32 v64, v64
	v_exp_f32_e32 v65, v65
	v_add_f32_e32 v130, v130, v58
	v_add_f32_e32 v130, v130, v59
	v_add_f32_e32 v130, v130, v60
	v_add_f32_e32 v130, v130, v61
	v_add_f32_e32 v130, v130, v62
	v_add_f32_e32 v130, v130, v63
	v_add_f32_e32 v130, v130, v64
	v_add_f32_e32 v130, v130, v65
	v_cvt_pk_bf16_f32 v46, v58, v59
	v_cvt_pk_bf16_f32 v47, v60, v61
	v_cvt_pk_bf16_f32 v48, v62, v63
	v_cvt_pk_bf16_f32 v49, v64, v65
	s_nop 0
	s_waitcnt lgkmcnt(2)
	v_mfma_f32_32x32x16_bf16 v[18:33], v[90:93], v[46:49], v[18:33]
	s_waitcnt lgkmcnt(0)
	v_mfma_f32_32x32x16_bf16 v[2:17], v[94:97], v[46:49], v[2:17]
	s_add_i32 s35, s35, 64
	v_add_u32_e32 v131, 0x100, v131
	s_cmp_eq_u32 s31, s39
	s_cbranch_scc1 .LBB0_1339
	s_branch .LBB0_1266
